# adds: residual RMW epilogue loads batched (16 row loads in flight instead of serialized round trips); wf8 activation reloads issued right after their LDS store (1.0-half prefetch distance)
# speedup vs baseline: 1.0436x; 1.0138x over previous
.LBB0_280:
	v_readfirstlane_b32 s100, v148
	v_readfirstlane_b32 s101, v149
	s_mov_b64 s[10:11], 0x1000
	s_nop 3
	v_subrev_u32_e32 v244, s100, v148
	s_sub_u32 s100, s100, 0x70080
	s_subb_u32 s101, s101, 0
	v_add_u32_e32 v245, 0x10000, v244
	v_add_u32_e32 v246, 0x20000, v244
	v_add_u32_e32 v247, 0x30000, v244
	v_add_u32_e32 v248, 0x40000, v244
	v_add_u32_e32 v249, 0x50000, v244
	v_add_u32_e32 v200, 0x60000, v244
	v_add_u32_e32 v201, 0x70000, v244
	global_load_dwordx4 v[180:183], v244, s[100:101]
	global_load_dwordx4 v[188:191], v245, s[100:101]
	global_load_dwordx4 v[192:195], v246, s[100:101]
	global_load_dwordx4 v[196:199], v247, s[100:101]
	global_load_dwordx4 v[228:231], v248, s[100:101]
	global_load_dwordx4 v[232:235], v249, s[100:101]
	global_load_dwordx4 v[236:239], v200, s[100:101]
	global_load_dwordx4 v[240:243], v201, s[100:101]
.Lwf8_l2_top:
	s_cmp_ge_u32 s5, 14
	s_cbranch_scc1 .Lwf8_l2_pen
	ds_read_b128 v[156:159], v128
	ds_read_b128 v[160:163], v128 offset:4608
	ds_read_b128 v[164:167], v128 offset:9216
	ds_read_b128 v[168:171], v128 offset:13824
	s_waitcnt vmcnt(11) lgkmcnt(3)
	v_mfma_f32_32x32x16_bf16 v[112:127], v[142:145], v[156:159], v[112:127]
	ds_read_b128 v[172:175], v128 offset:18432
	s_waitcnt lgkmcnt(3)
	v_mfma_f32_32x32x16_bf16 v[96:111], v[142:145], v[160:163], v[96:111]
	ds_read_b128 v[184:187], v128 offset:23040
	s_add_u32 s100, s100, 0x80
	s_addc_u32 s101, s101, 0
	s_waitcnt lgkmcnt(3)
	v_mfma_f32_32x32x16_bf16 v[80:95], v[142:145], v[164:167], v[80:95]
	ds_read_b128 v[156:159], v128 offset:27648
	s_waitcnt lgkmcnt(3)
	v_mfma_f32_32x32x16_bf16 v[64:79], v[142:145], v[168:171], v[64:79]
	ds_read_b128 v[160:163], v128 offset:32256
	s_waitcnt lgkmcnt(3)
	v_mfma_f32_32x32x16_bf16 v[48:63], v[142:145], v[172:175], v[48:63]
	ds_read_b128 v[164:167], v128 offset:32
	s_waitcnt lgkmcnt(3)
	v_mfma_f32_32x32x16_bf16 v[32:47], v[142:145], v[184:187], v[32:47]
	ds_read_b128 v[168:171], v128 offset:4640
	s_waitcnt lgkmcnt(3)
	v_mfma_f32_32x32x16_bf16 v[16:31], v[142:145], v[156:159], v[16:31]
	ds_read_b128 v[172:175], v128 offset:9248
	s_waitcnt lgkmcnt(3)
	v_mfma_f32_32x32x16_bf16 v[0:15], v[142:145], v[160:163], v[0:15]
	ds_read_b128 v[184:187], v128 offset:13856
	global_load_dwordx4 v[142:145], v[150:151], off offset:-2048
	s_waitcnt vmcnt(11) lgkmcnt(3)
	v_mfma_f32_32x32x16_bf16 v[112:127], v[138:141], v[164:167], v[112:127]
	ds_read_b128 v[156:159], v128 offset:18464
	s_waitcnt lgkmcnt(3)
	v_mfma_f32_32x32x16_bf16 v[96:111], v[138:141], v[168:171], v[96:111]
	ds_read_b128 v[160:163], v128 offset:23072
	s_waitcnt lgkmcnt(3)
	v_mfma_f32_32x32x16_bf16 v[80:95], v[138:141], v[172:175], v[80:95]
	ds_read_b128 v[164:167], v128 offset:27680
	s_waitcnt lgkmcnt(3)
	v_mfma_f32_32x32x16_bf16 v[64:79], v[138:141], v[184:187], v[64:79]
	ds_read_b128 v[168:171], v128 offset:32288
	s_waitcnt lgkmcnt(3)
	v_mfma_f32_32x32x16_bf16 v[48:63], v[138:141], v[156:159], v[48:63]
	ds_read_b128 v[172:175], v128 offset:64
	s_waitcnt lgkmcnt(3)
	v_mfma_f32_32x32x16_bf16 v[32:47], v[138:141], v[160:163], v[32:47]
	ds_read_b128 v[184:187], v128 offset:4672
	s_waitcnt lgkmcnt(3)
	v_mfma_f32_32x32x16_bf16 v[16:31], v[138:141], v[164:167], v[16:31]
	ds_read_b128 v[156:159], v128 offset:9280
	s_waitcnt lgkmcnt(3)
	v_mfma_f32_32x32x16_bf16 v[0:15], v[138:141], v[168:171], v[0:15]
	ds_read_b128 v[160:163], v128 offset:13888
	global_load_dwordx4 v[138:141], v[150:151], off offset:-1024
	s_waitcnt vmcnt(11) lgkmcnt(3)
	v_mfma_f32_32x32x16_bf16 v[112:127], v[134:137], v[172:175], v[112:127]
	ds_read_b128 v[164:167], v128 offset:18496
	s_waitcnt lgkmcnt(3)
	v_mfma_f32_32x32x16_bf16 v[96:111], v[134:137], v[184:187], v[96:111]
	ds_read_b128 v[168:171], v128 offset:23104
	s_waitcnt lgkmcnt(3)
	v_mfma_f32_32x32x16_bf16 v[80:95], v[134:137], v[156:159], v[80:95]
	ds_read_b128 v[172:175], v128 offset:27712
	s_waitcnt lgkmcnt(3)
	v_mfma_f32_32x32x16_bf16 v[64:79], v[134:137], v[160:163], v[64:79]
	ds_read_b128 v[184:187], v128 offset:32320
	s_waitcnt lgkmcnt(3)
	v_mfma_f32_32x32x16_bf16 v[48:63], v[134:137], v[164:167], v[48:63]
	ds_read_b128 v[156:159], v128 offset:96
	s_waitcnt lgkmcnt(3)
	v_mfma_f32_32x32x16_bf16 v[32:47], v[134:137], v[168:171], v[32:47]
	ds_read_b128 v[160:163], v128 offset:4704
	s_waitcnt lgkmcnt(3)
	v_mfma_f32_32x32x16_bf16 v[16:31], v[134:137], v[172:175], v[16:31]
	ds_read_b128 v[164:167], v128 offset:9312
	s_waitcnt lgkmcnt(3)
	v_mfma_f32_32x32x16_bf16 v[0:15], v[134:137], v[184:187], v[0:15]
	ds_read_b128 v[168:171], v128 offset:13920
	global_load_dwordx4 v[134:137], v[150:151], off
	s_waitcnt vmcnt(3) lgkmcnt(3)
	v_mfma_f32_32x32x16_bf16 v[112:127], v[130:133], v[156:159], v[112:127]
	ds_read_b128 v[172:175], v128 offset:18528
	ds_write_b128 v152, v[180:183] offset:36864
	global_load_dwordx4 v[180:183], v244, s[100:101]
	s_waitcnt lgkmcnt(4)
	v_mfma_f32_32x32x16_bf16 v[96:111], v[130:133], v[160:163], v[96:111]
	ds_read_b128 v[184:187], v128 offset:23136
	ds_write_b128 v152, v[188:191] offset:41472
	global_load_dwordx4 v[188:191], v245, s[100:101]
	s_waitcnt lgkmcnt(5)
	v_mfma_f32_32x32x16_bf16 v[80:95], v[130:133], v[164:167], v[80:95]
	ds_read_b128 v[156:159], v128 offset:27744
	ds_write_b128 v152, v[192:195] offset:46080
	global_load_dwordx4 v[192:195], v246, s[100:101]
	s_waitcnt lgkmcnt(6)
	v_mfma_f32_32x32x16_bf16 v[64:79], v[130:133], v[168:171], v[64:79]
	ds_read_b128 v[160:163], v128 offset:32352
	ds_write_b128 v152, v[196:199] offset:50688
	global_load_dwordx4 v[196:199], v247, s[100:101]
	s_waitcnt lgkmcnt(7)
	v_mfma_f32_32x32x16_bf16 v[48:63], v[130:133], v[172:175], v[48:63]
	ds_write_b128 v152, v[228:231] offset:55296
	global_load_dwordx4 v[228:231], v248, s[100:101]
	s_waitcnt lgkmcnt(6)
	v_mfma_f32_32x32x16_bf16 v[32:47], v[130:133], v[184:187], v[32:47]
	ds_write_b128 v152, v[232:235] offset:59904
	global_load_dwordx4 v[232:235], v249, s[100:101]
	s_waitcnt lgkmcnt(5)
	v_mfma_f32_32x32x16_bf16 v[16:31], v[130:133], v[156:159], v[16:31]
	ds_write_b128 v152, v[236:239] offset:64512
	global_load_dwordx4 v[236:239], v200, s[100:101]
	s_waitcnt lgkmcnt(4)
	v_mfma_f32_32x32x16_bf16 v[0:15], v[130:133], v[160:163], v[0:15]
	ds_write_b128 v153, v[240:243] offset:32256
	global_load_dwordx4 v[240:243], v201, s[100:101]
	global_load_dwordx4 v[130:133], v[150:151], off offset:1024
	v_lshl_add_u64 v[150:151], v[150:151], 0, s[10:11]
	s_waitcnt lgkmcnt(0)
	s_barrier
	ds_read_b128 v[156:159], v128 offset:36864
	ds_read_b128 v[160:163], v128 offset:41472
	ds_read_b128 v[164:167], v128 offset:46080
	ds_read_b128 v[168:171], v128 offset:50688
	s_waitcnt vmcnt(11) lgkmcnt(3)
	v_mfma_f32_32x32x16_bf16 v[112:127], v[142:145], v[156:159], v[112:127]
	ds_read_b128 v[172:175], v128 offset:55296
	s_waitcnt lgkmcnt(3)
	v_mfma_f32_32x32x16_bf16 v[96:111], v[142:145], v[160:163], v[96:111]
	ds_read_b128 v[184:187], v128 offset:59904
	s_add_u32 s100, s100, 0x80
	s_addc_u32 s101, s101, 0
	s_waitcnt lgkmcnt(3)
	v_mfma_f32_32x32x16_bf16 v[80:95], v[142:145], v[164:167], v[80:95]
	ds_read_b128 v[156:159], v128 offset:64512
	s_waitcnt lgkmcnt(3)
	v_mfma_f32_32x32x16_bf16 v[64:79], v[142:145], v[168:171], v[64:79]
	ds_read_b128 v[160:163], v154 offset:32256
	s_waitcnt lgkmcnt(3)
	v_mfma_f32_32x32x16_bf16 v[48:63], v[142:145], v[172:175], v[48:63]
	ds_read_b128 v[164:167], v128 offset:36896
	s_waitcnt lgkmcnt(3)
	v_mfma_f32_32x32x16_bf16 v[32:47], v[142:145], v[184:187], v[32:47]
	ds_read_b128 v[168:171], v128 offset:41504
	s_waitcnt lgkmcnt(3)
	v_mfma_f32_32x32x16_bf16 v[16:31], v[142:145], v[156:159], v[16:31]
	ds_read_b128 v[172:175], v128 offset:46112
	s_waitcnt lgkmcnt(3)
	v_mfma_f32_32x32x16_bf16 v[0:15], v[142:145], v[160:163], v[0:15]
	ds_read_b128 v[184:187], v128 offset:50720
	global_load_dwordx4 v[142:145], v[150:151], off offset:-2048
	s_waitcnt vmcnt(11) lgkmcnt(3)
	v_mfma_f32_32x32x16_bf16 v[112:127], v[138:141], v[164:167], v[112:127]
	ds_read_b128 v[156:159], v128 offset:55328
	s_waitcnt lgkmcnt(3)
	v_mfma_f32_32x32x16_bf16 v[96:111], v[138:141], v[168:171], v[96:111]
	ds_read_b128 v[160:163], v128 offset:59936
	s_waitcnt lgkmcnt(3)
	v_mfma_f32_32x32x16_bf16 v[80:95], v[138:141], v[172:175], v[80:95]
	ds_read_b128 v[164:167], v128 offset:64544
	s_waitcnt lgkmcnt(3)
	v_mfma_f32_32x32x16_bf16 v[64:79], v[138:141], v[184:187], v[64:79]
	ds_read_b128 v[168:171], v154 offset:32288
	s_waitcnt lgkmcnt(3)
	v_mfma_f32_32x32x16_bf16 v[48:63], v[138:141], v[156:159], v[48:63]
	ds_read_b128 v[172:175], v128 offset:36928
	s_waitcnt lgkmcnt(3)
	v_mfma_f32_32x32x16_bf16 v[32:47], v[138:141], v[160:163], v[32:47]
	ds_read_b128 v[184:187], v128 offset:41536
	s_waitcnt lgkmcnt(3)
	v_mfma_f32_32x32x16_bf16 v[16:31], v[138:141], v[164:167], v[16:31]
	ds_read_b128 v[156:159], v128 offset:46144
	s_waitcnt lgkmcnt(3)
	v_mfma_f32_32x32x16_bf16 v[0:15], v[138:141], v[168:171], v[0:15]
	ds_read_b128 v[160:163], v128 offset:50752
	global_load_dwordx4 v[138:141], v[150:151], off offset:-1024
	s_waitcnt vmcnt(11) lgkmcnt(3)
	v_mfma_f32_32x32x16_bf16 v[112:127], v[134:137], v[172:175], v[112:127]
	ds_read_b128 v[164:167], v128 offset:55360
	s_waitcnt lgkmcnt(3)
	v_mfma_f32_32x32x16_bf16 v[96:111], v[134:137], v[184:187], v[96:111]
	ds_read_b128 v[168:171], v128 offset:59968
	s_waitcnt lgkmcnt(3)
	v_mfma_f32_32x32x16_bf16 v[80:95], v[134:137], v[156:159], v[80:95]
	ds_read_b128 v[172:175], v128 offset:64576
	s_waitcnt lgkmcnt(3)
	v_mfma_f32_32x32x16_bf16 v[64:79], v[134:137], v[160:163], v[64:79]
	ds_read_b128 v[184:187], v154 offset:32320
	s_waitcnt lgkmcnt(3)
	v_mfma_f32_32x32x16_bf16 v[48:63], v[134:137], v[164:167], v[48:63]
	ds_read_b128 v[156:159], v128 offset:36960
	s_waitcnt lgkmcnt(3)
	v_mfma_f32_32x32x16_bf16 v[32:47], v[134:137], v[168:171], v[32:47]
	ds_read_b128 v[160:163], v128 offset:41568
	s_waitcnt lgkmcnt(3)
	v_mfma_f32_32x32x16_bf16 v[16:31], v[134:137], v[172:175], v[16:31]
	ds_read_b128 v[164:167], v128 offset:46176
	s_waitcnt lgkmcnt(3)
	v_mfma_f32_32x32x16_bf16 v[0:15], v[134:137], v[184:187], v[0:15]
	ds_read_b128 v[168:171], v128 offset:50784
	global_load_dwordx4 v[134:137], v[150:151], off
	s_waitcnt vmcnt(3) lgkmcnt(3)
	v_mfma_f32_32x32x16_bf16 v[112:127], v[130:133], v[156:159], v[112:127]
	ds_read_b128 v[172:175], v128 offset:55392
	ds_write_b128 v152, v[180:183]
	global_load_dwordx4 v[180:183], v244, s[100:101]
	s_waitcnt lgkmcnt(4)
	v_mfma_f32_32x32x16_bf16 v[96:111], v[130:133], v[160:163], v[96:111]
	ds_read_b128 v[184:187], v128 offset:60000
	ds_write_b128 v152, v[188:191] offset:4608
	global_load_dwordx4 v[188:191], v245, s[100:101]
	s_waitcnt lgkmcnt(5)
	v_mfma_f32_32x32x16_bf16 v[80:95], v[130:133], v[164:167], v[80:95]
	ds_read_b128 v[156:159], v128 offset:64608
	ds_write_b128 v152, v[192:195] offset:9216
	global_load_dwordx4 v[192:195], v246, s[100:101]
	s_waitcnt lgkmcnt(6)
	v_mfma_f32_32x32x16_bf16 v[64:79], v[130:133], v[168:171], v[64:79]
	ds_read_b128 v[160:163], v154 offset:32352
	ds_write_b128 v152, v[196:199] offset:13824
	global_load_dwordx4 v[196:199], v247, s[100:101]
	s_waitcnt lgkmcnt(7)
	v_mfma_f32_32x32x16_bf16 v[48:63], v[130:133], v[172:175], v[48:63]
	ds_write_b128 v152, v[228:231] offset:18432
	global_load_dwordx4 v[228:231], v248, s[100:101]
	s_waitcnt lgkmcnt(6)
	v_mfma_f32_32x32x16_bf16 v[32:47], v[130:133], v[184:187], v[32:47]
	ds_write_b128 v152, v[232:235] offset:23040
	global_load_dwordx4 v[232:235], v249, s[100:101]
	s_waitcnt lgkmcnt(5)
	v_mfma_f32_32x32x16_bf16 v[16:31], v[130:133], v[156:159], v[16:31]
	ds_write_b128 v152, v[236:239] offset:27648
	global_load_dwordx4 v[236:239], v200, s[100:101]
	s_waitcnt lgkmcnt(4)
	v_mfma_f32_32x32x16_bf16 v[0:15], v[130:133], v[160:163], v[0:15]
	ds_write_b128 v152, v[240:243] offset:32256
	global_load_dwordx4 v[240:243], v201, s[100:101]
	global_load_dwordx4 v[130:133], v[150:151], off offset:1024
	v_lshl_add_u64 v[150:151], v[150:151], 0, s[10:11]
	s_waitcnt lgkmcnt(0)
	s_barrier
	s_add_i32 s5, s5, 2
	s_branch .Lwf8_l2_top
.Lwf8_l2_pen:
	ds_read_b128 v[156:159], v128
	ds_read_b128 v[160:163], v128 offset:4608
	ds_read_b128 v[164:167], v128 offset:9216
	ds_read_b128 v[168:171], v128 offset:13824
	s_waitcnt vmcnt(11) lgkmcnt(3)
	v_mfma_f32_32x32x16_bf16 v[112:127], v[142:145], v[156:159], v[112:127]
	ds_read_b128 v[172:175], v128 offset:18432
	s_waitcnt lgkmcnt(3)
	v_mfma_f32_32x32x16_bf16 v[96:111], v[142:145], v[160:163], v[96:111]
	ds_read_b128 v[184:187], v128 offset:23040
	s_waitcnt lgkmcnt(3)
	v_mfma_f32_32x32x16_bf16 v[80:95], v[142:145], v[164:167], v[80:95]
	ds_read_b128 v[156:159], v128 offset:27648
	s_waitcnt lgkmcnt(3)
	v_mfma_f32_32x32x16_bf16 v[64:79], v[142:145], v[168:171], v[64:79]
	ds_read_b128 v[160:163], v128 offset:32256
	s_waitcnt lgkmcnt(3)
	v_mfma_f32_32x32x16_bf16 v[48:63], v[142:145], v[172:175], v[48:63]
	ds_read_b128 v[164:167], v128 offset:32
	s_waitcnt lgkmcnt(3)
	v_mfma_f32_32x32x16_bf16 v[32:47], v[142:145], v[184:187], v[32:47]
	ds_read_b128 v[168:171], v128 offset:4640
	s_waitcnt lgkmcnt(3)
	v_mfma_f32_32x32x16_bf16 v[16:31], v[142:145], v[156:159], v[16:31]
	ds_read_b128 v[172:175], v128 offset:9248
	s_waitcnt lgkmcnt(3)
	v_mfma_f32_32x32x16_bf16 v[0:15], v[142:145], v[160:163], v[0:15]
	ds_read_b128 v[184:187], v128 offset:13856
	global_load_dwordx4 v[142:145], v[150:151], off offset:-2048
	s_waitcnt vmcnt(11) lgkmcnt(3)
	v_mfma_f32_32x32x16_bf16 v[112:127], v[138:141], v[164:167], v[112:127]
	ds_read_b128 v[156:159], v128 offset:18464
	s_waitcnt lgkmcnt(3)
	v_mfma_f32_32x32x16_bf16 v[96:111], v[138:141], v[168:171], v[96:111]
	ds_read_b128 v[160:163], v128 offset:23072
	s_waitcnt lgkmcnt(3)
	v_mfma_f32_32x32x16_bf16 v[80:95], v[138:141], v[172:175], v[80:95]
	ds_read_b128 v[164:167], v128 offset:27680
	s_waitcnt lgkmcnt(3)
	v_mfma_f32_32x32x16_bf16 v[64:79], v[138:141], v[184:187], v[64:79]
	ds_read_b128 v[168:171], v128 offset:32288
	s_waitcnt lgkmcnt(3)
	v_mfma_f32_32x32x16_bf16 v[48:63], v[138:141], v[156:159], v[48:63]
	ds_read_b128 v[172:175], v128 offset:64
	s_waitcnt lgkmcnt(3)
	v_mfma_f32_32x32x16_bf16 v[32:47], v[138:141], v[160:163], v[32:47]
	ds_read_b128 v[184:187], v128 offset:4672
	s_waitcnt lgkmcnt(3)
	v_mfma_f32_32x32x16_bf16 v[16:31], v[138:141], v[164:167], v[16:31]
	ds_read_b128 v[156:159], v128 offset:9280
	s_waitcnt lgkmcnt(3)
	v_mfma_f32_32x32x16_bf16 v[0:15], v[138:141], v[168:171], v[0:15]
	ds_read_b128 v[160:163], v128 offset:13888
	global_load_dwordx4 v[138:141], v[150:151], off offset:-1024
	s_waitcnt vmcnt(11) lgkmcnt(3)
	v_mfma_f32_32x32x16_bf16 v[112:127], v[134:137], v[172:175], v[112:127]
	ds_read_b128 v[164:167], v128 offset:18496
	s_waitcnt lgkmcnt(3)
	v_mfma_f32_32x32x16_bf16 v[96:111], v[134:137], v[184:187], v[96:111]
	ds_read_b128 v[168:171], v128 offset:23104
	s_waitcnt lgkmcnt(3)
	v_mfma_f32_32x32x16_bf16 v[80:95], v[134:137], v[156:159], v[80:95]
	ds_read_b128 v[172:175], v128 offset:27712
	s_waitcnt lgkmcnt(3)
	v_mfma_f32_32x32x16_bf16 v[64:79], v[134:137], v[160:163], v[64:79]
	ds_read_b128 v[184:187], v128 offset:32320
	s_waitcnt lgkmcnt(3)
	v_mfma_f32_32x32x16_bf16 v[48:63], v[134:137], v[164:167], v[48:63]
	ds_read_b128 v[156:159], v128 offset:96
	s_waitcnt lgkmcnt(3)
	v_mfma_f32_32x32x16_bf16 v[32:47], v[134:137], v[168:171], v[32:47]
	ds_read_b128 v[160:163], v128 offset:4704
	s_waitcnt lgkmcnt(3)
	v_mfma_f32_32x32x16_bf16 v[16:31], v[134:137], v[172:175], v[16:31]
	ds_read_b128 v[164:167], v128 offset:9312
	s_waitcnt lgkmcnt(3)
	v_mfma_f32_32x32x16_bf16 v[0:15], v[134:137], v[184:187], v[0:15]
	ds_read_b128 v[168:171], v128 offset:13920
	global_load_dwordx4 v[134:137], v[150:151], off
	s_waitcnt vmcnt(3) lgkmcnt(3)
	v_mfma_f32_32x32x16_bf16 v[112:127], v[130:133], v[156:159], v[112:127]
	ds_read_b128 v[172:175], v128 offset:18528
	ds_write_b128 v152, v[180:183] offset:36864
	s_waitcnt lgkmcnt(4)
	v_mfma_f32_32x32x16_bf16 v[96:111], v[130:133], v[160:163], v[96:111]
	ds_read_b128 v[184:187], v128 offset:23136
	ds_write_b128 v152, v[188:191] offset:41472
	s_waitcnt lgkmcnt(5)
	v_mfma_f32_32x32x16_bf16 v[80:95], v[130:133], v[164:167], v[80:95]
	ds_read_b128 v[156:159], v128 offset:27744
	ds_write_b128 v152, v[192:195] offset:46080
	s_waitcnt lgkmcnt(6)
	v_mfma_f32_32x32x16_bf16 v[64:79], v[130:133], v[168:171], v[64:79]
	ds_read_b128 v[160:163], v128 offset:32352
	ds_write_b128 v152, v[196:199] offset:50688
	s_waitcnt lgkmcnt(7)
	v_mfma_f32_32x32x16_bf16 v[48:63], v[130:133], v[172:175], v[48:63]
	ds_write_b128 v152, v[228:231] offset:55296
	s_waitcnt lgkmcnt(6)
	v_mfma_f32_32x32x16_bf16 v[32:47], v[130:133], v[184:187], v[32:47]
	ds_write_b128 v152, v[232:235] offset:59904
	s_waitcnt lgkmcnt(5)
	v_mfma_f32_32x32x16_bf16 v[16:31], v[130:133], v[156:159], v[16:31]
	ds_write_b128 v152, v[236:239] offset:64512
	s_waitcnt lgkmcnt(4)
	v_mfma_f32_32x32x16_bf16 v[0:15], v[130:133], v[160:163], v[0:15]
	ds_write_b128 v153, v[240:243] offset:32256
	global_load_dwordx4 v[130:133], v[150:151], off offset:1024
	v_lshl_add_u64 v[150:151], v[150:151], 0, s[10:11]
	s_waitcnt lgkmcnt(0)
	s_barrier
	ds_read_b128 v[156:159], v128 offset:36864
	ds_read_b128 v[160:163], v128 offset:41472
	ds_read_b128 v[164:167], v128 offset:46080
	ds_read_b128 v[168:171], v128 offset:50688
	s_waitcnt vmcnt(3) lgkmcnt(3)
	v_mfma_f32_32x32x16_bf16 v[112:127], v[142:145], v[156:159], v[112:127]
	ds_read_b128 v[172:175], v128 offset:55296
	s_waitcnt lgkmcnt(3)
	v_mfma_f32_32x32x16_bf16 v[96:111], v[142:145], v[160:163], v[96:111]
	ds_read_b128 v[184:187], v128 offset:59904
	s_waitcnt lgkmcnt(3)
	v_mfma_f32_32x32x16_bf16 v[80:95], v[142:145], v[164:167], v[80:95]
	ds_read_b128 v[156:159], v128 offset:64512
	s_waitcnt lgkmcnt(3)
	v_mfma_f32_32x32x16_bf16 v[64:79], v[142:145], v[168:171], v[64:79]
	ds_read_b128 v[160:163], v154 offset:32256
	s_waitcnt lgkmcnt(3)
	v_mfma_f32_32x32x16_bf16 v[48:63], v[142:145], v[172:175], v[48:63]
	ds_read_b128 v[164:167], v128 offset:36896
	s_waitcnt lgkmcnt(3)
	v_mfma_f32_32x32x16_bf16 v[32:47], v[142:145], v[184:187], v[32:47]
	ds_read_b128 v[168:171], v128 offset:41504
	s_waitcnt lgkmcnt(3)
	v_mfma_f32_32x32x16_bf16 v[16:31], v[142:145], v[156:159], v[16:31]
	ds_read_b128 v[172:175], v128 offset:46112
	s_waitcnt lgkmcnt(3)
	v_mfma_f32_32x32x16_bf16 v[0:15], v[142:145], v[160:163], v[0:15]
	ds_read_b128 v[184:187], v128 offset:50720
	s_waitcnt vmcnt(2) lgkmcnt(3)
	v_mfma_f32_32x32x16_bf16 v[112:127], v[138:141], v[164:167], v[112:127]
	ds_read_b128 v[156:159], v128 offset:55328
	s_waitcnt lgkmcnt(3)
	v_mfma_f32_32x32x16_bf16 v[96:111], v[138:141], v[168:171], v[96:111]
	ds_read_b128 v[160:163], v128 offset:59936
	s_waitcnt lgkmcnt(3)
	v_mfma_f32_32x32x16_bf16 v[80:95], v[138:141], v[172:175], v[80:95]
	ds_read_b128 v[164:167], v128 offset:64544
	s_waitcnt lgkmcnt(3)
	v_mfma_f32_32x32x16_bf16 v[64:79], v[138:141], v[184:187], v[64:79]
	ds_read_b128 v[168:171], v154 offset:32288
	s_waitcnt lgkmcnt(3)
	v_mfma_f32_32x32x16_bf16 v[48:63], v[138:141], v[156:159], v[48:63]
	ds_read_b128 v[172:175], v128 offset:36928
	s_waitcnt lgkmcnt(3)
	v_mfma_f32_32x32x16_bf16 v[32:47], v[138:141], v[160:163], v[32:47]
	ds_read_b128 v[184:187], v128 offset:41536
	s_waitcnt lgkmcnt(3)
	v_mfma_f32_32x32x16_bf16 v[16:31], v[138:141], v[164:167], v[16:31]
	ds_read_b128 v[156:159], v128 offset:46144
	s_waitcnt lgkmcnt(3)
	v_mfma_f32_32x32x16_bf16 v[0:15], v[138:141], v[168:171], v[0:15]
	ds_read_b128 v[160:163], v128 offset:50752
	s_waitcnt vmcnt(1) lgkmcnt(3)
	v_mfma_f32_32x32x16_bf16 v[112:127], v[134:137], v[172:175], v[112:127]
	ds_read_b128 v[164:167], v128 offset:55360
	s_waitcnt lgkmcnt(3)
	v_mfma_f32_32x32x16_bf16 v[96:111], v[134:137], v[184:187], v[96:111]
	ds_read_b128 v[168:171], v128 offset:59968
	s_waitcnt lgkmcnt(3)
	v_mfma_f32_32x32x16_bf16 v[80:95], v[134:137], v[156:159], v[80:95]
	ds_read_b128 v[172:175], v128 offset:64576
	s_waitcnt lgkmcnt(3)
	v_mfma_f32_32x32x16_bf16 v[64:79], v[134:137], v[160:163], v[64:79]
	ds_read_b128 v[184:187], v154 offset:32320
	s_waitcnt lgkmcnt(3)
	v_mfma_f32_32x32x16_bf16 v[48:63], v[134:137], v[164:167], v[48:63]
	ds_read_b128 v[156:159], v128 offset:36960
	s_waitcnt lgkmcnt(3)
	v_mfma_f32_32x32x16_bf16 v[32:47], v[134:137], v[168:171], v[32:47]
	ds_read_b128 v[160:163], v128 offset:41568
	s_waitcnt lgkmcnt(3)
	v_mfma_f32_32x32x16_bf16 v[16:31], v[134:137], v[172:175], v[16:31]
	ds_read_b128 v[164:167], v128 offset:46176
	s_waitcnt lgkmcnt(3)
	v_mfma_f32_32x32x16_bf16 v[0:15], v[134:137], v[184:187], v[0:15]
	ds_read_b128 v[168:171], v128 offset:50784
	s_waitcnt vmcnt(0) lgkmcnt(3)
	v_mfma_f32_32x32x16_bf16 v[112:127], v[130:133], v[156:159], v[112:127]
	ds_read_b128 v[172:175], v128 offset:55392
	s_waitcnt lgkmcnt(3)
	v_mfma_f32_32x32x16_bf16 v[96:111], v[130:133], v[160:163], v[96:111]
	ds_read_b128 v[184:187], v128 offset:60000
	s_waitcnt lgkmcnt(3)
	v_mfma_f32_32x32x16_bf16 v[80:95], v[130:133], v[164:167], v[80:95]
	ds_read_b128 v[156:159], v128 offset:64608
	s_waitcnt lgkmcnt(3)
	v_mfma_f32_32x32x16_bf16 v[64:79], v[130:133], v[168:171], v[64:79]
	ds_read_b128 v[160:163], v154 offset:32352
	s_waitcnt lgkmcnt(3)
	v_mfma_f32_32x32x16_bf16 v[48:63], v[130:133], v[172:175], v[48:63]
	s_waitcnt lgkmcnt(2)
	v_mfma_f32_32x32x16_bf16 v[32:47], v[130:133], v[184:187], v[32:47]
	s_waitcnt lgkmcnt(1)
	v_mfma_f32_32x32x16_bf16 v[16:31], v[130:133], v[156:159], v[16:31]
	s_waitcnt lgkmcnt(0)
	v_mfma_f32_32x32x16_bf16 v[0:15], v[130:133], v[160:163], v[0:15]
	s_waitcnt lgkmcnt(0)
	s_barrier
	s_nop 7
	s_nop 7
	s_branch .LBB0_282

.LBB0_1794:
	v_readfirstlane_b32 s100, v148
	v_readfirstlane_b32 s101, v149
	s_mov_b64 s[16:17], 0x1000
	s_nop 3
	v_subrev_u32_e32 v244, s100, v148
	s_sub_u32 s100, s100, 0x70080
	s_subb_u32 s101, s101, 0
	v_add_u32_e32 v245, 0x10000, v244
	v_add_u32_e32 v246, 0x20000, v244
	v_add_u32_e32 v247, 0x30000, v244
	v_add_u32_e32 v248, 0x40000, v244
	v_add_u32_e32 v249, 0x50000, v244
	v_add_u32_e32 v200, 0x60000, v244
	v_add_u32_e32 v201, 0x70000, v244
	global_load_dwordx4 v[180:183], v244, s[100:101]
	global_load_dwordx4 v[188:191], v245, s[100:101]
	global_load_dwordx4 v[192:195], v246, s[100:101]
	global_load_dwordx4 v[196:199], v247, s[100:101]
	global_load_dwordx4 v[228:231], v248, s[100:101]
	global_load_dwordx4 v[232:235], v249, s[100:101]
	global_load_dwordx4 v[236:239], v200, s[100:101]
	global_load_dwordx4 v[240:243], v201, s[100:101]
.Lwf8_l6a_top:
	s_cmp_ge_u32 s7, 14
	s_cbranch_scc1 .Lwf8_l6a_pen
	ds_read_b128 v[156:159], v152
	ds_read_b128 v[160:163], v152 offset:4608
	ds_read_b128 v[164:167], v152 offset:9216
	ds_read_b128 v[168:171], v152 offset:13824
	s_waitcnt vmcnt(11) lgkmcnt(3)
	v_mfma_f32_32x32x16_bf16 v[112:127], v[142:145], v[156:159], v[112:127]
	ds_read_b128 v[172:175], v152 offset:18432
	s_waitcnt lgkmcnt(3)
	v_mfma_f32_32x32x16_bf16 v[96:111], v[142:145], v[160:163], v[96:111]
	ds_read_b128 v[184:187], v152 offset:23040
	s_add_u32 s100, s100, 0x80
	s_addc_u32 s101, s101, 0
	s_waitcnt lgkmcnt(3)
	v_mfma_f32_32x32x16_bf16 v[80:95], v[142:145], v[164:167], v[80:95]
	ds_read_b128 v[156:159], v152 offset:27648
	s_waitcnt lgkmcnt(3)
	v_mfma_f32_32x32x16_bf16 v[64:79], v[142:145], v[168:171], v[64:79]
	ds_read_b128 v[160:163], v152 offset:32256
	s_waitcnt lgkmcnt(3)
	v_mfma_f32_32x32x16_bf16 v[48:63], v[142:145], v[172:175], v[48:63]
	ds_read_b128 v[164:167], v152 offset:32
	s_waitcnt lgkmcnt(3)
	v_mfma_f32_32x32x16_bf16 v[32:47], v[142:145], v[184:187], v[32:47]
	ds_read_b128 v[168:171], v152 offset:4640
	s_waitcnt lgkmcnt(3)
	v_mfma_f32_32x32x16_bf16 v[16:31], v[142:145], v[156:159], v[16:31]
	ds_read_b128 v[172:175], v152 offset:9248
	s_waitcnt lgkmcnt(3)
	v_mfma_f32_32x32x16_bf16 v[0:15], v[142:145], v[160:163], v[0:15]
	ds_read_b128 v[184:187], v152 offset:13856
	global_load_dwordx4 v[142:145], v[150:151], off offset:-2048
	s_waitcnt vmcnt(11) lgkmcnt(3)
	v_mfma_f32_32x32x16_bf16 v[112:127], v[138:141], v[164:167], v[112:127]
	ds_read_b128 v[156:159], v152 offset:18464
	s_waitcnt lgkmcnt(3)
	v_mfma_f32_32x32x16_bf16 v[96:111], v[138:141], v[168:171], v[96:111]
	ds_read_b128 v[160:163], v152 offset:23072
	s_waitcnt lgkmcnt(3)
	v_mfma_f32_32x32x16_bf16 v[80:95], v[138:141], v[172:175], v[80:95]
	ds_read_b128 v[164:167], v152 offset:27680
	s_waitcnt lgkmcnt(3)
	v_mfma_f32_32x32x16_bf16 v[64:79], v[138:141], v[184:187], v[64:79]
	ds_read_b128 v[168:171], v152 offset:32288
	s_waitcnt lgkmcnt(3)
	v_mfma_f32_32x32x16_bf16 v[48:63], v[138:141], v[156:159], v[48:63]
	ds_read_b128 v[172:175], v152 offset:64
	s_waitcnt lgkmcnt(3)
	v_mfma_f32_32x32x16_bf16 v[32:47], v[138:141], v[160:163], v[32:47]
	ds_read_b128 v[184:187], v152 offset:4672
	s_waitcnt lgkmcnt(3)
	v_mfma_f32_32x32x16_bf16 v[16:31], v[138:141], v[164:167], v[16:31]
	ds_read_b128 v[156:159], v152 offset:9280
	s_waitcnt lgkmcnt(3)
	v_mfma_f32_32x32x16_bf16 v[0:15], v[138:141], v[168:171], v[0:15]
	ds_read_b128 v[160:163], v152 offset:13888
	global_load_dwordx4 v[138:141], v[150:151], off offset:-1024
	s_waitcnt vmcnt(11) lgkmcnt(3)
	v_mfma_f32_32x32x16_bf16 v[112:127], v[134:137], v[172:175], v[112:127]
	ds_read_b128 v[164:167], v152 offset:18496
	s_waitcnt lgkmcnt(3)
	v_mfma_f32_32x32x16_bf16 v[96:111], v[134:137], v[184:187], v[96:111]
	ds_read_b128 v[168:171], v152 offset:23104
	s_waitcnt lgkmcnt(3)
	v_mfma_f32_32x32x16_bf16 v[80:95], v[134:137], v[156:159], v[80:95]
	ds_read_b128 v[172:175], v152 offset:27712
	s_waitcnt lgkmcnt(3)
	v_mfma_f32_32x32x16_bf16 v[64:79], v[134:137], v[160:163], v[64:79]
	ds_read_b128 v[184:187], v152 offset:32320
	s_waitcnt lgkmcnt(3)
	v_mfma_f32_32x32x16_bf16 v[48:63], v[134:137], v[164:167], v[48:63]
	ds_read_b128 v[156:159], v152 offset:96
	s_waitcnt lgkmcnt(3)
	v_mfma_f32_32x32x16_bf16 v[32:47], v[134:137], v[168:171], v[32:47]
	ds_read_b128 v[160:163], v152 offset:4704
	s_waitcnt lgkmcnt(3)
	v_mfma_f32_32x32x16_bf16 v[16:31], v[134:137], v[172:175], v[16:31]
	ds_read_b128 v[164:167], v152 offset:9312
	s_waitcnt lgkmcnt(3)
	v_mfma_f32_32x32x16_bf16 v[0:15], v[134:137], v[184:187], v[0:15]
	ds_read_b128 v[168:171], v152 offset:13920
	global_load_dwordx4 v[134:137], v[150:151], off
	s_waitcnt vmcnt(3) lgkmcnt(3)
	v_mfma_f32_32x32x16_bf16 v[112:127], v[130:133], v[156:159], v[112:127]
	ds_read_b128 v[172:175], v152 offset:18528
	ds_write_b128 v128, v[180:183] offset:36864
	global_load_dwordx4 v[180:183], v244, s[100:101]
	s_waitcnt lgkmcnt(4)
	v_mfma_f32_32x32x16_bf16 v[96:111], v[130:133], v[160:163], v[96:111]
	ds_read_b128 v[184:187], v152 offset:23136
	ds_write_b128 v128, v[188:191] offset:41472
	global_load_dwordx4 v[188:191], v245, s[100:101]
	s_waitcnt lgkmcnt(5)
	v_mfma_f32_32x32x16_bf16 v[80:95], v[130:133], v[164:167], v[80:95]
	ds_read_b128 v[156:159], v152 offset:27744
	ds_write_b128 v128, v[192:195] offset:46080
	global_load_dwordx4 v[192:195], v246, s[100:101]
	s_waitcnt lgkmcnt(6)
	v_mfma_f32_32x32x16_bf16 v[64:79], v[130:133], v[168:171], v[64:79]
	ds_read_b128 v[160:163], v152 offset:32352
	ds_write_b128 v128, v[196:199] offset:50688
	global_load_dwordx4 v[196:199], v247, s[100:101]
	s_waitcnt lgkmcnt(7)
	v_mfma_f32_32x32x16_bf16 v[48:63], v[130:133], v[172:175], v[48:63]
	ds_write_b128 v128, v[228:231] offset:55296
	global_load_dwordx4 v[228:231], v248, s[100:101]
	s_waitcnt lgkmcnt(6)
	v_mfma_f32_32x32x16_bf16 v[32:47], v[130:133], v[184:187], v[32:47]
	ds_write_b128 v128, v[232:235] offset:59904
	global_load_dwordx4 v[232:235], v249, s[100:101]
	s_waitcnt lgkmcnt(5)
	v_mfma_f32_32x32x16_bf16 v[16:31], v[130:133], v[156:159], v[16:31]
	ds_write_b128 v128, v[236:239] offset:64512
	global_load_dwordx4 v[236:239], v200, s[100:101]
	s_waitcnt lgkmcnt(4)
	v_mfma_f32_32x32x16_bf16 v[0:15], v[130:133], v[160:163], v[0:15]
	ds_write_b128 v153, v[240:243] offset:32256
	global_load_dwordx4 v[240:243], v201, s[100:101]
	global_load_dwordx4 v[130:133], v[150:151], off offset:1024
	v_lshl_add_u64 v[150:151], v[150:151], 0, s[16:17]
	s_waitcnt lgkmcnt(0)
	s_barrier
	ds_read_b128 v[156:159], v152 offset:36864
	ds_read_b128 v[160:163], v152 offset:41472
	ds_read_b128 v[164:167], v152 offset:46080
	ds_read_b128 v[168:171], v152 offset:50688
	s_waitcnt vmcnt(11) lgkmcnt(3)
	v_mfma_f32_32x32x16_bf16 v[112:127], v[142:145], v[156:159], v[112:127]
	ds_read_b128 v[172:175], v152 offset:55296
	s_waitcnt lgkmcnt(3)
	v_mfma_f32_32x32x16_bf16 v[96:111], v[142:145], v[160:163], v[96:111]
	ds_read_b128 v[184:187], v152 offset:59904
	s_add_u32 s100, s100, 0x80
	s_addc_u32 s101, s101, 0
	s_waitcnt lgkmcnt(3)
	v_mfma_f32_32x32x16_bf16 v[80:95], v[142:145], v[164:167], v[80:95]
	ds_read_b128 v[156:159], v152 offset:64512
	s_waitcnt lgkmcnt(3)
	v_mfma_f32_32x32x16_bf16 v[64:79], v[142:145], v[168:171], v[64:79]
	ds_read_b128 v[160:163], v154 offset:32256
	s_waitcnt lgkmcnt(3)
	v_mfma_f32_32x32x16_bf16 v[48:63], v[142:145], v[172:175], v[48:63]
	ds_read_b128 v[164:167], v152 offset:36896
	s_waitcnt lgkmcnt(3)
	v_mfma_f32_32x32x16_bf16 v[32:47], v[142:145], v[184:187], v[32:47]
	ds_read_b128 v[168:171], v152 offset:41504
	s_waitcnt lgkmcnt(3)
	v_mfma_f32_32x32x16_bf16 v[16:31], v[142:145], v[156:159], v[16:31]
	ds_read_b128 v[172:175], v152 offset:46112
	s_waitcnt lgkmcnt(3)
	v_mfma_f32_32x32x16_bf16 v[0:15], v[142:145], v[160:163], v[0:15]
	ds_read_b128 v[184:187], v152 offset:50720
	global_load_dwordx4 v[142:145], v[150:151], off offset:-2048
	s_waitcnt vmcnt(11) lgkmcnt(3)
	v_mfma_f32_32x32x16_bf16 v[112:127], v[138:141], v[164:167], v[112:127]
	ds_read_b128 v[156:159], v152 offset:55328
	s_waitcnt lgkmcnt(3)
	v_mfma_f32_32x32x16_bf16 v[96:111], v[138:141], v[168:171], v[96:111]
	ds_read_b128 v[160:163], v152 offset:59936
	s_waitcnt lgkmcnt(3)
	v_mfma_f32_32x32x16_bf16 v[80:95], v[138:141], v[172:175], v[80:95]
	ds_read_b128 v[164:167], v152 offset:64544
	s_waitcnt lgkmcnt(3)
	v_mfma_f32_32x32x16_bf16 v[64:79], v[138:141], v[184:187], v[64:79]
	ds_read_b128 v[168:171], v154 offset:32288
	s_waitcnt lgkmcnt(3)
	v_mfma_f32_32x32x16_bf16 v[48:63], v[138:141], v[156:159], v[48:63]
	ds_read_b128 v[172:175], v152 offset:36928
	s_waitcnt lgkmcnt(3)
	v_mfma_f32_32x32x16_bf16 v[32:47], v[138:141], v[160:163], v[32:47]
	ds_read_b128 v[184:187], v152 offset:41536
	s_waitcnt lgkmcnt(3)
	v_mfma_f32_32x32x16_bf16 v[16:31], v[138:141], v[164:167], v[16:31]
	ds_read_b128 v[156:159], v152 offset:46144
	s_waitcnt lgkmcnt(3)
	v_mfma_f32_32x32x16_bf16 v[0:15], v[138:141], v[168:171], v[0:15]
	ds_read_b128 v[160:163], v152 offset:50752
	global_load_dwordx4 v[138:141], v[150:151], off offset:-1024
	s_waitcnt vmcnt(11) lgkmcnt(3)
	v_mfma_f32_32x32x16_bf16 v[112:127], v[134:137], v[172:175], v[112:127]
	ds_read_b128 v[164:167], v152 offset:55360
	s_waitcnt lgkmcnt(3)
	v_mfma_f32_32x32x16_bf16 v[96:111], v[134:137], v[184:187], v[96:111]
	ds_read_b128 v[168:171], v152 offset:59968
	s_waitcnt lgkmcnt(3)
	v_mfma_f32_32x32x16_bf16 v[80:95], v[134:137], v[156:159], v[80:95]
	ds_read_b128 v[172:175], v152 offset:64576
	s_waitcnt lgkmcnt(3)
	v_mfma_f32_32x32x16_bf16 v[64:79], v[134:137], v[160:163], v[64:79]
	ds_read_b128 v[184:187], v154 offset:32320
	s_waitcnt lgkmcnt(3)
	v_mfma_f32_32x32x16_bf16 v[48:63], v[134:137], v[164:167], v[48:63]
	ds_read_b128 v[156:159], v152 offset:36960
	s_waitcnt lgkmcnt(3)
	v_mfma_f32_32x32x16_bf16 v[32:47], v[134:137], v[168:171], v[32:47]
	ds_read_b128 v[160:163], v152 offset:41568
	s_waitcnt lgkmcnt(3)
	v_mfma_f32_32x32x16_bf16 v[16:31], v[134:137], v[172:175], v[16:31]
	ds_read_b128 v[164:167], v152 offset:46176
	s_waitcnt lgkmcnt(3)
	v_mfma_f32_32x32x16_bf16 v[0:15], v[134:137], v[184:187], v[0:15]
	ds_read_b128 v[168:171], v152 offset:50784
	global_load_dwordx4 v[134:137], v[150:151], off
	s_waitcnt vmcnt(3) lgkmcnt(3)
	v_mfma_f32_32x32x16_bf16 v[112:127], v[130:133], v[156:159], v[112:127]
	ds_read_b128 v[172:175], v152 offset:55392
	ds_write_b128 v128, v[180:183]
	global_load_dwordx4 v[180:183], v244, s[100:101]
	s_waitcnt lgkmcnt(4)
	v_mfma_f32_32x32x16_bf16 v[96:111], v[130:133], v[160:163], v[96:111]
	ds_read_b128 v[184:187], v152 offset:60000
	ds_write_b128 v128, v[188:191] offset:4608
	global_load_dwordx4 v[188:191], v245, s[100:101]
	s_waitcnt lgkmcnt(5)
	v_mfma_f32_32x32x16_bf16 v[80:95], v[130:133], v[164:167], v[80:95]
	ds_read_b128 v[156:159], v152 offset:64608
	ds_write_b128 v128, v[192:195] offset:9216
	global_load_dwordx4 v[192:195], v246, s[100:101]
	s_waitcnt lgkmcnt(6)
	v_mfma_f32_32x32x16_bf16 v[64:79], v[130:133], v[168:171], v[64:79]
	ds_read_b128 v[160:163], v154 offset:32352
	ds_write_b128 v128, v[196:199] offset:13824
	global_load_dwordx4 v[196:199], v247, s[100:101]
	s_waitcnt lgkmcnt(7)
	v_mfma_f32_32x32x16_bf16 v[48:63], v[130:133], v[172:175], v[48:63]
	ds_write_b128 v128, v[228:231] offset:18432
	global_load_dwordx4 v[228:231], v248, s[100:101]
	s_waitcnt lgkmcnt(6)
	v_mfma_f32_32x32x16_bf16 v[32:47], v[130:133], v[184:187], v[32:47]
	ds_write_b128 v128, v[232:235] offset:23040
	global_load_dwordx4 v[232:235], v249, s[100:101]
	s_waitcnt lgkmcnt(5)
	v_mfma_f32_32x32x16_bf16 v[16:31], v[130:133], v[156:159], v[16:31]
	ds_write_b128 v128, v[236:239] offset:27648
	global_load_dwordx4 v[236:239], v200, s[100:101]
	s_waitcnt lgkmcnt(4)
	v_mfma_f32_32x32x16_bf16 v[0:15], v[130:133], v[160:163], v[0:15]
	ds_write_b128 v128, v[240:243] offset:32256
	global_load_dwordx4 v[240:243], v201, s[100:101]
	global_load_dwordx4 v[130:133], v[150:151], off offset:1024
	v_lshl_add_u64 v[150:151], v[150:151], 0, s[16:17]
	s_waitcnt lgkmcnt(0)
	s_barrier
	s_add_i32 s7, s7, 2
	s_branch .Lwf8_l6a_top
.Lwf8_l6a_pen:
	ds_read_b128 v[156:159], v152
	ds_read_b128 v[160:163], v152 offset:4608
	ds_read_b128 v[164:167], v152 offset:9216
	ds_read_b128 v[168:171], v152 offset:13824
	s_waitcnt vmcnt(11) lgkmcnt(3)
	v_mfma_f32_32x32x16_bf16 v[112:127], v[142:145], v[156:159], v[112:127]
	ds_read_b128 v[172:175], v152 offset:18432
	s_waitcnt lgkmcnt(3)
	v_mfma_f32_32x32x16_bf16 v[96:111], v[142:145], v[160:163], v[96:111]
	ds_read_b128 v[184:187], v152 offset:23040
	s_waitcnt lgkmcnt(3)
	v_mfma_f32_32x32x16_bf16 v[80:95], v[142:145], v[164:167], v[80:95]
	ds_read_b128 v[156:159], v152 offset:27648
	s_waitcnt lgkmcnt(3)
	v_mfma_f32_32x32x16_bf16 v[64:79], v[142:145], v[168:171], v[64:79]
	ds_read_b128 v[160:163], v152 offset:32256
	s_waitcnt lgkmcnt(3)
	v_mfma_f32_32x32x16_bf16 v[48:63], v[142:145], v[172:175], v[48:63]
	ds_read_b128 v[164:167], v152 offset:32
	s_waitcnt lgkmcnt(3)
	v_mfma_f32_32x32x16_bf16 v[32:47], v[142:145], v[184:187], v[32:47]
	ds_read_b128 v[168:171], v152 offset:4640
	s_waitcnt lgkmcnt(3)
	v_mfma_f32_32x32x16_bf16 v[16:31], v[142:145], v[156:159], v[16:31]
	ds_read_b128 v[172:175], v152 offset:9248
	s_waitcnt lgkmcnt(3)
	v_mfma_f32_32x32x16_bf16 v[0:15], v[142:145], v[160:163], v[0:15]
	ds_read_b128 v[184:187], v152 offset:13856
	global_load_dwordx4 v[142:145], v[150:151], off offset:-2048
	s_waitcnt vmcnt(11) lgkmcnt(3)
	v_mfma_f32_32x32x16_bf16 v[112:127], v[138:141], v[164:167], v[112:127]
	ds_read_b128 v[156:159], v152 offset:18464
	s_waitcnt lgkmcnt(3)
	v_mfma_f32_32x32x16_bf16 v[96:111], v[138:141], v[168:171], v[96:111]
	ds_read_b128 v[160:163], v152 offset:23072
	s_waitcnt lgkmcnt(3)
	v_mfma_f32_32x32x16_bf16 v[80:95], v[138:141], v[172:175], v[80:95]
	ds_read_b128 v[164:167], v152 offset:27680
	s_waitcnt lgkmcnt(3)
	v_mfma_f32_32x32x16_bf16 v[64:79], v[138:141], v[184:187], v[64:79]
	ds_read_b128 v[168:171], v152 offset:32288
	s_waitcnt lgkmcnt(3)
	v_mfma_f32_32x32x16_bf16 v[48:63], v[138:141], v[156:159], v[48:63]
	ds_read_b128 v[172:175], v152 offset:64
	s_waitcnt lgkmcnt(3)
	v_mfma_f32_32x32x16_bf16 v[32:47], v[138:141], v[160:163], v[32:47]
	ds_read_b128 v[184:187], v152 offset:4672
	s_waitcnt lgkmcnt(3)
	v_mfma_f32_32x32x16_bf16 v[16:31], v[138:141], v[164:167], v[16:31]
	ds_read_b128 v[156:159], v152 offset:9280
	s_waitcnt lgkmcnt(3)
	v_mfma_f32_32x32x16_bf16 v[0:15], v[138:141], v[168:171], v[0:15]
	ds_read_b128 v[160:163], v152 offset:13888
	global_load_dwordx4 v[138:141], v[150:151], off offset:-1024
	s_waitcnt vmcnt(11) lgkmcnt(3)
	v_mfma_f32_32x32x16_bf16 v[112:127], v[134:137], v[172:175], v[112:127]
	ds_read_b128 v[164:167], v152 offset:18496
	s_waitcnt lgkmcnt(3)
	v_mfma_f32_32x32x16_bf16 v[96:111], v[134:137], v[184:187], v[96:111]
	ds_read_b128 v[168:171], v152 offset:23104
	s_waitcnt lgkmcnt(3)
	v_mfma_f32_32x32x16_bf16 v[80:95], v[134:137], v[156:159], v[80:95]
	ds_read_b128 v[172:175], v152 offset:27712
	s_waitcnt lgkmcnt(3)
	v_mfma_f32_32x32x16_bf16 v[64:79], v[134:137], v[160:163], v[64:79]
	ds_read_b128 v[184:187], v152 offset:32320
	s_waitcnt lgkmcnt(3)
	v_mfma_f32_32x32x16_bf16 v[48:63], v[134:137], v[164:167], v[48:63]
	ds_read_b128 v[156:159], v152 offset:96
	s_waitcnt lgkmcnt(3)
	v_mfma_f32_32x32x16_bf16 v[32:47], v[134:137], v[168:171], v[32:47]
	ds_read_b128 v[160:163], v152 offset:4704
	s_waitcnt lgkmcnt(3)
	v_mfma_f32_32x32x16_bf16 v[16:31], v[134:137], v[172:175], v[16:31]
	ds_read_b128 v[164:167], v152 offset:9312
	s_waitcnt lgkmcnt(3)
	v_mfma_f32_32x32x16_bf16 v[0:15], v[134:137], v[184:187], v[0:15]
	ds_read_b128 v[168:171], v152 offset:13920
	global_load_dwordx4 v[134:137], v[150:151], off
	s_waitcnt vmcnt(3) lgkmcnt(3)
	v_mfma_f32_32x32x16_bf16 v[112:127], v[130:133], v[156:159], v[112:127]
	ds_read_b128 v[172:175], v152 offset:18528
	ds_write_b128 v128, v[180:183] offset:36864
	s_waitcnt lgkmcnt(4)
	v_mfma_f32_32x32x16_bf16 v[96:111], v[130:133], v[160:163], v[96:111]
	ds_read_b128 v[184:187], v152 offset:23136
	ds_write_b128 v128, v[188:191] offset:41472
	s_waitcnt lgkmcnt(5)
	v_mfma_f32_32x32x16_bf16 v[80:95], v[130:133], v[164:167], v[80:95]
	ds_read_b128 v[156:159], v152 offset:27744
	ds_write_b128 v128, v[192:195] offset:46080
	s_waitcnt lgkmcnt(6)
	v_mfma_f32_32x32x16_bf16 v[64:79], v[130:133], v[168:171], v[64:79]
	ds_read_b128 v[160:163], v152 offset:32352
	ds_write_b128 v128, v[196:199] offset:50688
	s_waitcnt lgkmcnt(7)
	v_mfma_f32_32x32x16_bf16 v[48:63], v[130:133], v[172:175], v[48:63]
	ds_write_b128 v128, v[228:231] offset:55296
	s_waitcnt lgkmcnt(6)
	v_mfma_f32_32x32x16_bf16 v[32:47], v[130:133], v[184:187], v[32:47]
	ds_write_b128 v128, v[232:235] offset:59904
	s_waitcnt lgkmcnt(5)
	v_mfma_f32_32x32x16_bf16 v[16:31], v[130:133], v[156:159], v[16:31]
	ds_write_b128 v128, v[236:239] offset:64512
	s_waitcnt lgkmcnt(4)
	v_mfma_f32_32x32x16_bf16 v[0:15], v[130:133], v[160:163], v[0:15]
	ds_write_b128 v153, v[240:243] offset:32256
	global_load_dwordx4 v[130:133], v[150:151], off offset:1024
	v_lshl_add_u64 v[150:151], v[150:151], 0, s[16:17]
	s_waitcnt lgkmcnt(0)
	s_barrier
	ds_read_b128 v[156:159], v152 offset:36864
	ds_read_b128 v[160:163], v152 offset:41472
	ds_read_b128 v[164:167], v152 offset:46080
	ds_read_b128 v[168:171], v152 offset:50688
	s_waitcnt vmcnt(3) lgkmcnt(3)
	v_mfma_f32_32x32x16_bf16 v[112:127], v[142:145], v[156:159], v[112:127]
	ds_read_b128 v[172:175], v152 offset:55296
	s_waitcnt lgkmcnt(3)
	v_mfma_f32_32x32x16_bf16 v[96:111], v[142:145], v[160:163], v[96:111]
	ds_read_b128 v[184:187], v152 offset:59904
	s_waitcnt lgkmcnt(3)
	v_mfma_f32_32x32x16_bf16 v[80:95], v[142:145], v[164:167], v[80:95]
	ds_read_b128 v[156:159], v152 offset:64512
	s_waitcnt lgkmcnt(3)
	v_mfma_f32_32x32x16_bf16 v[64:79], v[142:145], v[168:171], v[64:79]
	ds_read_b128 v[160:163], v154 offset:32256
	s_waitcnt lgkmcnt(3)
	v_mfma_f32_32x32x16_bf16 v[48:63], v[142:145], v[172:175], v[48:63]
	ds_read_b128 v[164:167], v152 offset:36896
	s_waitcnt lgkmcnt(3)
	v_mfma_f32_32x32x16_bf16 v[32:47], v[142:145], v[184:187], v[32:47]
	ds_read_b128 v[168:171], v152 offset:41504
	s_waitcnt lgkmcnt(3)
	v_mfma_f32_32x32x16_bf16 v[16:31], v[142:145], v[156:159], v[16:31]
	ds_read_b128 v[172:175], v152 offset:46112
	s_waitcnt lgkmcnt(3)
	v_mfma_f32_32x32x16_bf16 v[0:15], v[142:145], v[160:163], v[0:15]
	ds_read_b128 v[184:187], v152 offset:50720
	s_waitcnt vmcnt(2) lgkmcnt(3)
	v_mfma_f32_32x32x16_bf16 v[112:127], v[138:141], v[164:167], v[112:127]
	ds_read_b128 v[156:159], v152 offset:55328
	s_waitcnt lgkmcnt(3)
	v_mfma_f32_32x32x16_bf16 v[96:111], v[138:141], v[168:171], v[96:111]
	ds_read_b128 v[160:163], v152 offset:59936
	s_waitcnt lgkmcnt(3)
	v_mfma_f32_32x32x16_bf16 v[80:95], v[138:141], v[172:175], v[80:95]
	ds_read_b128 v[164:167], v152 offset:64544
	s_waitcnt lgkmcnt(3)
	v_mfma_f32_32x32x16_bf16 v[64:79], v[138:141], v[184:187], v[64:79]
	ds_read_b128 v[168:171], v154 offset:32288
	s_waitcnt lgkmcnt(3)
	v_mfma_f32_32x32x16_bf16 v[48:63], v[138:141], v[156:159], v[48:63]
	ds_read_b128 v[172:175], v152 offset:36928
	s_waitcnt lgkmcnt(3)
	v_mfma_f32_32x32x16_bf16 v[32:47], v[138:141], v[160:163], v[32:47]
	ds_read_b128 v[184:187], v152 offset:41536
	s_waitcnt lgkmcnt(3)
	v_mfma_f32_32x32x16_bf16 v[16:31], v[138:141], v[164:167], v[16:31]
	ds_read_b128 v[156:159], v152 offset:46144
	s_waitcnt lgkmcnt(3)
	v_mfma_f32_32x32x16_bf16 v[0:15], v[138:141], v[168:171], v[0:15]
	ds_read_b128 v[160:163], v152 offset:50752
	s_waitcnt vmcnt(1) lgkmcnt(3)
	v_mfma_f32_32x32x16_bf16 v[112:127], v[134:137], v[172:175], v[112:127]
	ds_read_b128 v[164:167], v152 offset:55360
	s_waitcnt lgkmcnt(3)
	v_mfma_f32_32x32x16_bf16 v[96:111], v[134:137], v[184:187], v[96:111]
	ds_read_b128 v[168:171], v152 offset:59968
	s_waitcnt lgkmcnt(3)
	v_mfma_f32_32x32x16_bf16 v[80:95], v[134:137], v[156:159], v[80:95]
	ds_read_b128 v[172:175], v152 offset:64576
	s_waitcnt lgkmcnt(3)
	v_mfma_f32_32x32x16_bf16 v[64:79], v[134:137], v[160:163], v[64:79]
	ds_read_b128 v[184:187], v154 offset:32320
	s_waitcnt lgkmcnt(3)
	v_mfma_f32_32x32x16_bf16 v[48:63], v[134:137], v[164:167], v[48:63]
	ds_read_b128 v[156:159], v152 offset:36960
	s_waitcnt lgkmcnt(3)
	v_mfma_f32_32x32x16_bf16 v[32:47], v[134:137], v[168:171], v[32:47]
	ds_read_b128 v[160:163], v152 offset:41568
	s_waitcnt lgkmcnt(3)
	v_mfma_f32_32x32x16_bf16 v[16:31], v[134:137], v[172:175], v[16:31]
	ds_read_b128 v[164:167], v152 offset:46176
	s_waitcnt lgkmcnt(3)
	v_mfma_f32_32x32x16_bf16 v[0:15], v[134:137], v[184:187], v[0:15]
	ds_read_b128 v[168:171], v152 offset:50784
	s_waitcnt vmcnt(0) lgkmcnt(3)
	v_mfma_f32_32x32x16_bf16 v[112:127], v[130:133], v[156:159], v[112:127]
	ds_read_b128 v[172:175], v152 offset:55392
	s_waitcnt lgkmcnt(3)
	v_mfma_f32_32x32x16_bf16 v[96:111], v[130:133], v[160:163], v[96:111]
	ds_read_b128 v[184:187], v152 offset:60000
	s_waitcnt lgkmcnt(3)
	v_mfma_f32_32x32x16_bf16 v[80:95], v[130:133], v[164:167], v[80:95]
	ds_read_b128 v[156:159], v152 offset:64608
	s_waitcnt lgkmcnt(3)
	v_mfma_f32_32x32x16_bf16 v[64:79], v[130:133], v[168:171], v[64:79]
	ds_read_b128 v[160:163], v154 offset:32352
	s_waitcnt lgkmcnt(3)
	v_mfma_f32_32x32x16_bf16 v[48:63], v[130:133], v[172:175], v[48:63]
	s_waitcnt lgkmcnt(2)
	v_mfma_f32_32x32x16_bf16 v[32:47], v[130:133], v[184:187], v[32:47]
	s_waitcnt lgkmcnt(1)
	v_mfma_f32_32x32x16_bf16 v[16:31], v[130:133], v[156:159], v[16:31]
	s_waitcnt lgkmcnt(0)
	v_mfma_f32_32x32x16_bf16 v[0:15], v[130:133], v[160:163], v[0:15]
	s_waitcnt lgkmcnt(0)
	s_barrier
	s_nop 7
	s_nop 7
	s_branch .LBB0_1789

.LBB0_1938:
	v_add_u32_e32 v16, s2, v6
	v_ashrrev_i32_e32 v17, 31, v16
	v_lshlrev_b64 v[12:13], 12, v[16:17]
	v_lshl_add_u64 v[24:25], v[4:5], 0, v[12:13]
	v_mov_b32_e32 v26, v24
	v_mov_b32_e32 v27, v25
	s_mov_b64 s[16:17], 0x8000
	s_cmp_eq_u32 s14, 0x80
	s_cbranch_scc0 .Lrmw7_half
	global_load_dwordx4 v[64:67], v[24:25], off
	v_lshl_add_u64 v[24:25], v[24:25], 0, s[16:17]
	global_load_dwordx4 v[68:71], v[24:25], off
	v_lshl_add_u64 v[24:25], v[24:25], 0, s[16:17]
	global_load_dwordx4 v[72:75], v[24:25], off
	v_lshl_add_u64 v[24:25], v[24:25], 0, s[16:17]
	global_load_dwordx4 v[76:79], v[24:25], off
	v_lshl_add_u64 v[24:25], v[24:25], 0, s[16:17]
	global_load_dwordx4 v[80:83], v[24:25], off
	v_lshl_add_u64 v[24:25], v[24:25], 0, s[16:17]
	global_load_dwordx4 v[88:91], v[24:25], off
	v_lshl_add_u64 v[24:25], v[24:25], 0, s[16:17]
	global_load_dwordx4 v[92:95], v[24:25], off
	v_lshl_add_u64 v[24:25], v[24:25], 0, s[16:17]
	global_load_dwordx4 v[96:99], v[24:25], off
	v_lshl_add_u64 v[24:25], v[24:25], 0, s[16:17]
	global_load_dwordx4 v[100:103], v[24:25], off
	v_lshl_add_u64 v[24:25], v[24:25], 0, s[16:17]
	global_load_dwordx4 v[104:107], v[24:25], off
	v_lshl_add_u64 v[24:25], v[24:25], 0, s[16:17]
	global_load_dwordx4 v[108:111], v[24:25], off
	v_lshl_add_u64 v[24:25], v[24:25], 0, s[16:17]
	global_load_dwordx4 v[130:133], v[24:25], off
	v_lshl_add_u64 v[24:25], v[24:25], 0, s[16:17]
	global_load_dwordx4 v[134:137], v[24:25], off
	v_lshl_add_u64 v[24:25], v[24:25], 0, s[16:17]
	global_load_dwordx4 v[138:141], v[24:25], off
	v_lshl_add_u64 v[24:25], v[24:25], 0, s[16:17]
	global_load_dwordx4 v[142:145], v[24:25], off
	v_lshl_add_u64 v[24:25], v[24:25], 0, s[16:17]
	global_load_dwordx4 v[146:149], v[24:25], off
	v_lshl_add_u64 v[24:25], v[24:25], 0, s[16:17]
	ds_read_b128 v[8:11], v7
	ds_read_b128 v[12:15], v7 offset:4224
	ds_read_b128 v[16:19], v7 offset:8448
	ds_read_b128 v[20:23], v7 offset:12672
	s_waitcnt vmcnt(15) lgkmcnt(3)
	v_pk_fma_f32 v[64:65], v[0:1], v[8:9], v[64:65]
	v_pk_fma_f32 v[66:67], v[2:3], v[10:11], v[66:67]
	global_store_dwordx4 v[26:27], v[64:67], off
	v_lshl_add_u64 v[26:27], v[26:27], 0, s[16:17]
	s_waitcnt vmcnt(15) lgkmcnt(2)
	v_pk_fma_f32 v[68:69], v[0:1], v[12:13], v[68:69]
	v_pk_fma_f32 v[70:71], v[2:3], v[14:15], v[70:71]
	global_store_dwordx4 v[26:27], v[68:71], off
	v_lshl_add_u64 v[26:27], v[26:27], 0, s[16:17]
	s_waitcnt vmcnt(15) lgkmcnt(1)
	v_pk_fma_f32 v[72:73], v[0:1], v[16:17], v[72:73]
	v_pk_fma_f32 v[74:75], v[2:3], v[18:19], v[74:75]
	global_store_dwordx4 v[26:27], v[72:75], off
	v_lshl_add_u64 v[26:27], v[26:27], 0, s[16:17]
	s_waitcnt vmcnt(15) lgkmcnt(0)
	v_pk_fma_f32 v[76:77], v[0:1], v[20:21], v[76:77]
	v_pk_fma_f32 v[78:79], v[2:3], v[22:23], v[78:79]
	global_store_dwordx4 v[26:27], v[76:79], off
	v_lshl_add_u64 v[26:27], v[26:27], 0, s[16:17]
	ds_read_b128 v[8:11], v7 offset:16896
	ds_read_b128 v[12:15], v7 offset:21120
	ds_read_b128 v[16:19], v7 offset:25344
	ds_read_b128 v[20:23], v7 offset:29568
	s_waitcnt vmcnt(15) lgkmcnt(3)
	v_pk_fma_f32 v[80:81], v[0:1], v[8:9], v[80:81]
	v_pk_fma_f32 v[82:83], v[2:3], v[10:11], v[82:83]
	global_store_dwordx4 v[26:27], v[80:83], off
	v_lshl_add_u64 v[26:27], v[26:27], 0, s[16:17]
	s_waitcnt vmcnt(15) lgkmcnt(2)
	v_pk_fma_f32 v[88:89], v[0:1], v[12:13], v[88:89]
	v_pk_fma_f32 v[90:91], v[2:3], v[14:15], v[90:91]
	global_store_dwordx4 v[26:27], v[88:91], off
	v_lshl_add_u64 v[26:27], v[26:27], 0, s[16:17]
	s_waitcnt vmcnt(15) lgkmcnt(1)
	v_pk_fma_f32 v[92:93], v[0:1], v[16:17], v[92:93]
	v_pk_fma_f32 v[94:95], v[2:3], v[18:19], v[94:95]
	global_store_dwordx4 v[26:27], v[92:95], off
	v_lshl_add_u64 v[26:27], v[26:27], 0, s[16:17]
	s_waitcnt vmcnt(15) lgkmcnt(0)
	v_pk_fma_f32 v[96:97], v[0:1], v[20:21], v[96:97]
	v_pk_fma_f32 v[98:99], v[2:3], v[22:23], v[98:99]
	global_store_dwordx4 v[26:27], v[96:99], off
	v_lshl_add_u64 v[26:27], v[26:27], 0, s[16:17]
	ds_read_b128 v[8:11], v7 offset:33792
	ds_read_b128 v[12:15], v7 offset:38016
	ds_read_b128 v[16:19], v7 offset:42240
	ds_read_b128 v[20:23], v7 offset:46464
	s_waitcnt vmcnt(15) lgkmcnt(3)
	v_pk_fma_f32 v[100:101], v[0:1], v[8:9], v[100:101]
	v_pk_fma_f32 v[102:103], v[2:3], v[10:11], v[102:103]
	global_store_dwordx4 v[26:27], v[100:103], off
	v_lshl_add_u64 v[26:27], v[26:27], 0, s[16:17]
	s_waitcnt vmcnt(15) lgkmcnt(2)
	v_pk_fma_f32 v[104:105], v[0:1], v[12:13], v[104:105]
	v_pk_fma_f32 v[106:107], v[2:3], v[14:15], v[106:107]
	global_store_dwordx4 v[26:27], v[104:107], off
	v_lshl_add_u64 v[26:27], v[26:27], 0, s[16:17]
	s_waitcnt vmcnt(15) lgkmcnt(1)
	v_pk_fma_f32 v[108:109], v[0:1], v[16:17], v[108:109]
	v_pk_fma_f32 v[110:111], v[2:3], v[18:19], v[110:111]
	global_store_dwordx4 v[26:27], v[108:111], off
	v_lshl_add_u64 v[26:27], v[26:27], 0, s[16:17]
	s_waitcnt vmcnt(15) lgkmcnt(0)
	v_pk_fma_f32 v[130:131], v[0:1], v[20:21], v[130:131]
	v_pk_fma_f32 v[132:133], v[2:3], v[22:23], v[132:133]
	global_store_dwordx4 v[26:27], v[130:133], off
	v_lshl_add_u64 v[26:27], v[26:27], 0, s[16:17]
	ds_read_b128 v[8:11], v7 offset:50688
	ds_read_b128 v[12:15], v7 offset:54912
	ds_read_b128 v[16:19], v7 offset:59136
	ds_read_b128 v[20:23], v7 offset:63360
	s_waitcnt vmcnt(15) lgkmcnt(3)
	v_pk_fma_f32 v[134:135], v[0:1], v[8:9], v[134:135]
	v_pk_fma_f32 v[136:137], v[2:3], v[10:11], v[136:137]
	global_store_dwordx4 v[26:27], v[134:137], off
	v_lshl_add_u64 v[26:27], v[26:27], 0, s[16:17]
	s_waitcnt vmcnt(15) lgkmcnt(2)
	v_pk_fma_f32 v[138:139], v[0:1], v[12:13], v[138:139]
	v_pk_fma_f32 v[140:141], v[2:3], v[14:15], v[140:141]
	global_store_dwordx4 v[26:27], v[138:141], off
	v_lshl_add_u64 v[26:27], v[26:27], 0, s[16:17]
	s_waitcnt vmcnt(15) lgkmcnt(1)
	v_pk_fma_f32 v[142:143], v[0:1], v[16:17], v[142:143]
	v_pk_fma_f32 v[144:145], v[2:3], v[18:19], v[144:145]
	global_store_dwordx4 v[26:27], v[142:145], off
	v_lshl_add_u64 v[26:27], v[26:27], 0, s[16:17]
	s_waitcnt vmcnt(15) lgkmcnt(0)
	v_pk_fma_f32 v[146:147], v[0:1], v[20:21], v[146:147]
	v_pk_fma_f32 v[148:149], v[2:3], v[22:23], v[148:149]
	global_store_dwordx4 v[26:27], v[146:149], off
	v_lshl_add_u64 v[26:27], v[26:27], 0, s[16:17]
	s_branch .Lrmw7_done
.Lrmw7_half:
	global_load_dwordx4 v[64:67], v[24:25], off
	v_lshl_add_u64 v[24:25], v[24:25], 0, s[16:17]
	global_load_dwordx4 v[68:71], v[24:25], off
	v_lshl_add_u64 v[24:25], v[24:25], 0, s[16:17]
	global_load_dwordx4 v[72:75], v[24:25], off
	v_lshl_add_u64 v[24:25], v[24:25], 0, s[16:17]
	global_load_dwordx4 v[76:79], v[24:25], off
	v_lshl_add_u64 v[24:25], v[24:25], 0, s[16:17]
	global_load_dwordx4 v[80:83], v[24:25], off
	v_lshl_add_u64 v[24:25], v[24:25], 0, s[16:17]
	global_load_dwordx4 v[88:91], v[24:25], off
	v_lshl_add_u64 v[24:25], v[24:25], 0, s[16:17]
	global_load_dwordx4 v[92:95], v[24:25], off
	v_lshl_add_u64 v[24:25], v[24:25], 0, s[16:17]
	global_load_dwordx4 v[96:99], v[24:25], off
	v_lshl_add_u64 v[24:25], v[24:25], 0, s[16:17]
	ds_read_b128 v[8:11], v7
	ds_read_b128 v[12:15], v7 offset:4224
	ds_read_b128 v[16:19], v7 offset:8448
	ds_read_b128 v[20:23], v7 offset:12672
	s_waitcnt vmcnt(7) lgkmcnt(3)
	v_pk_fma_f32 v[64:65], v[0:1], v[8:9], v[64:65]
	v_pk_fma_f32 v[66:67], v[2:3], v[10:11], v[66:67]
	global_store_dwordx4 v[26:27], v[64:67], off
	v_lshl_add_u64 v[26:27], v[26:27], 0, s[16:17]
	s_waitcnt vmcnt(7) lgkmcnt(2)
	v_pk_fma_f32 v[68:69], v[0:1], v[12:13], v[68:69]
	v_pk_fma_f32 v[70:71], v[2:3], v[14:15], v[70:71]
	global_store_dwordx4 v[26:27], v[68:71], off
	v_lshl_add_u64 v[26:27], v[26:27], 0, s[16:17]
	s_waitcnt vmcnt(7) lgkmcnt(1)
	v_pk_fma_f32 v[72:73], v[0:1], v[16:17], v[72:73]
	v_pk_fma_f32 v[74:75], v[2:3], v[18:19], v[74:75]
	global_store_dwordx4 v[26:27], v[72:75], off
	v_lshl_add_u64 v[26:27], v[26:27], 0, s[16:17]
	s_waitcnt vmcnt(7) lgkmcnt(0)
	v_pk_fma_f32 v[76:77], v[0:1], v[20:21], v[76:77]
	v_pk_fma_f32 v[78:79], v[2:3], v[22:23], v[78:79]
	global_store_dwordx4 v[26:27], v[76:79], off
	v_lshl_add_u64 v[26:27], v[26:27], 0, s[16:17]
	ds_read_b128 v[8:11], v7 offset:16896
	ds_read_b128 v[12:15], v7 offset:21120
	ds_read_b128 v[16:19], v7 offset:25344
	ds_read_b128 v[20:23], v7 offset:29568
	s_waitcnt vmcnt(7) lgkmcnt(3)
	v_pk_fma_f32 v[80:81], v[0:1], v[8:9], v[80:81]
	v_pk_fma_f32 v[82:83], v[2:3], v[10:11], v[82:83]
	global_store_dwordx4 v[26:27], v[80:83], off
	v_lshl_add_u64 v[26:27], v[26:27], 0, s[16:17]
	s_waitcnt vmcnt(7) lgkmcnt(2)
	v_pk_fma_f32 v[88:89], v[0:1], v[12:13], v[88:89]
	v_pk_fma_f32 v[90:91], v[2:3], v[14:15], v[90:91]
	global_store_dwordx4 v[26:27], v[88:91], off
	v_lshl_add_u64 v[26:27], v[26:27], 0, s[16:17]
	s_waitcnt vmcnt(7) lgkmcnt(1)
	v_pk_fma_f32 v[92:93], v[0:1], v[16:17], v[92:93]
	v_pk_fma_f32 v[94:95], v[2:3], v[18:19], v[94:95]
	global_store_dwordx4 v[26:27], v[92:95], off
	v_lshl_add_u64 v[26:27], v[26:27], 0, s[16:17]
	s_waitcnt vmcnt(7) lgkmcnt(0)
	v_pk_fma_f32 v[96:97], v[0:1], v[20:21], v[96:97]
	v_pk_fma_f32 v[98:99], v[2:3], v[22:23], v[98:99]
	global_store_dwordx4 v[26:27], v[96:99], off
	v_lshl_add_u64 v[26:27], v[26:27], 0, s[16:17]
.Lrmw7_done:
	s_branch .LBB0_1927

.LBB0_2055:
	v_readfirstlane_b32 s100, v148
	v_readfirstlane_b32 s101, v149
	s_mov_b64 s[26:27], 0x1000
	s_nop 3
	v_subrev_u32_e32 v244, s100, v148
	s_sub_u32 s100, s100, 0x70080
	s_subb_u32 s101, s101, 0
	v_add_u32_e32 v245, 0x10000, v244
	v_add_u32_e32 v246, 0x20000, v244
	v_add_u32_e32 v247, 0x30000, v244
	v_add_u32_e32 v248, 0x40000, v244
	v_add_u32_e32 v249, 0x50000, v244
	v_add_u32_e32 v200, 0x60000, v244
	v_add_u32_e32 v201, 0x70000, v244
	global_load_dwordx4 v[180:183], v244, s[100:101]
	global_load_dwordx4 v[188:191], v245, s[100:101]
	global_load_dwordx4 v[192:195], v246, s[100:101]
	global_load_dwordx4 v[196:199], v247, s[100:101]
	global_load_dwordx4 v[228:231], v248, s[100:101]
	global_load_dwordx4 v[232:235], v249, s[100:101]
	global_load_dwordx4 v[236:239], v200, s[100:101]
	global_load_dwordx4 v[240:243], v201, s[100:101]
.Lwf8_l9_top:
	s_cmp_ge_u32 s13, 14
	s_cbranch_scc1 .Lwf8_l9_pen
	ds_read_b128 v[156:159], v152
	ds_read_b128 v[160:163], v152 offset:4608
	ds_read_b128 v[164:167], v152 offset:9216
	ds_read_b128 v[168:171], v152 offset:13824
	s_waitcnt vmcnt(11) lgkmcnt(3)
	v_mfma_f32_32x32x16_bf16 v[112:127], v[142:145], v[156:159], v[112:127]
	ds_read_b128 v[172:175], v152 offset:18432
	s_waitcnt lgkmcnt(3)
	v_mfma_f32_32x32x16_bf16 v[96:111], v[142:145], v[160:163], v[96:111]
	ds_read_b128 v[184:187], v152 offset:23040
	s_add_u32 s100, s100, 0x80
	s_addc_u32 s101, s101, 0
	s_waitcnt lgkmcnt(3)
	v_mfma_f32_32x32x16_bf16 v[80:95], v[142:145], v[164:167], v[80:95]
	ds_read_b128 v[156:159], v152 offset:27648
	s_waitcnt lgkmcnt(3)
	v_mfma_f32_32x32x16_bf16 v[64:79], v[142:145], v[168:171], v[64:79]
	ds_read_b128 v[160:163], v152 offset:32256
	s_waitcnt lgkmcnt(3)
	v_mfma_f32_32x32x16_bf16 v[48:63], v[142:145], v[172:175], v[48:63]
	ds_read_b128 v[164:167], v152 offset:32
	s_waitcnt lgkmcnt(3)
	v_mfma_f32_32x32x16_bf16 v[32:47], v[142:145], v[184:187], v[32:47]
	ds_read_b128 v[168:171], v152 offset:4640
	s_waitcnt lgkmcnt(3)
	v_mfma_f32_32x32x16_bf16 v[16:31], v[142:145], v[156:159], v[16:31]
	ds_read_b128 v[172:175], v152 offset:9248
	s_waitcnt lgkmcnt(3)
	v_mfma_f32_32x32x16_bf16 v[0:15], v[142:145], v[160:163], v[0:15]
	ds_read_b128 v[184:187], v152 offset:13856
	global_load_dwordx4 v[142:145], v[150:151], off offset:-2048
	s_waitcnt vmcnt(11) lgkmcnt(3)
	v_mfma_f32_32x32x16_bf16 v[112:127], v[138:141], v[164:167], v[112:127]
	ds_read_b128 v[156:159], v152 offset:18464
	s_waitcnt lgkmcnt(3)
	v_mfma_f32_32x32x16_bf16 v[96:111], v[138:141], v[168:171], v[96:111]
	ds_read_b128 v[160:163], v152 offset:23072
	s_waitcnt lgkmcnt(3)
	v_mfma_f32_32x32x16_bf16 v[80:95], v[138:141], v[172:175], v[80:95]
	ds_read_b128 v[164:167], v152 offset:27680
	s_waitcnt lgkmcnt(3)
	v_mfma_f32_32x32x16_bf16 v[64:79], v[138:141], v[184:187], v[64:79]
	ds_read_b128 v[168:171], v152 offset:32288
	s_waitcnt lgkmcnt(3)
	v_mfma_f32_32x32x16_bf16 v[48:63], v[138:141], v[156:159], v[48:63]
	ds_read_b128 v[172:175], v152 offset:64
	s_waitcnt lgkmcnt(3)
	v_mfma_f32_32x32x16_bf16 v[32:47], v[138:141], v[160:163], v[32:47]
	ds_read_b128 v[184:187], v152 offset:4672
	s_waitcnt lgkmcnt(3)
	v_mfma_f32_32x32x16_bf16 v[16:31], v[138:141], v[164:167], v[16:31]
	ds_read_b128 v[156:159], v152 offset:9280
	s_waitcnt lgkmcnt(3)
	v_mfma_f32_32x32x16_bf16 v[0:15], v[138:141], v[168:171], v[0:15]
	ds_read_b128 v[160:163], v152 offset:13888
	global_load_dwordx4 v[138:141], v[150:151], off offset:-1024
	s_waitcnt vmcnt(11) lgkmcnt(3)
	v_mfma_f32_32x32x16_bf16 v[112:127], v[134:137], v[172:175], v[112:127]
	ds_read_b128 v[164:167], v152 offset:18496
	s_waitcnt lgkmcnt(3)
	v_mfma_f32_32x32x16_bf16 v[96:111], v[134:137], v[184:187], v[96:111]
	ds_read_b128 v[168:171], v152 offset:23104
	s_waitcnt lgkmcnt(3)
	v_mfma_f32_32x32x16_bf16 v[80:95], v[134:137], v[156:159], v[80:95]
	ds_read_b128 v[172:175], v152 offset:27712
	s_waitcnt lgkmcnt(3)
	v_mfma_f32_32x32x16_bf16 v[64:79], v[134:137], v[160:163], v[64:79]
	ds_read_b128 v[184:187], v152 offset:32320
	s_waitcnt lgkmcnt(3)
	v_mfma_f32_32x32x16_bf16 v[48:63], v[134:137], v[164:167], v[48:63]
	ds_read_b128 v[156:159], v152 offset:96
	s_waitcnt lgkmcnt(3)
	v_mfma_f32_32x32x16_bf16 v[32:47], v[134:137], v[168:171], v[32:47]
	ds_read_b128 v[160:163], v152 offset:4704
	s_waitcnt lgkmcnt(3)
	v_mfma_f32_32x32x16_bf16 v[16:31], v[134:137], v[172:175], v[16:31]
	ds_read_b128 v[164:167], v152 offset:9312
	s_waitcnt lgkmcnt(3)
	v_mfma_f32_32x32x16_bf16 v[0:15], v[134:137], v[184:187], v[0:15]
	ds_read_b128 v[168:171], v152 offset:13920
	global_load_dwordx4 v[134:137], v[150:151], off
	s_waitcnt vmcnt(3) lgkmcnt(3)
	v_mfma_f32_32x32x16_bf16 v[112:127], v[130:133], v[156:159], v[112:127]
	ds_read_b128 v[172:175], v152 offset:18528
	ds_write_b128 v128, v[180:183] offset:36864
	global_load_dwordx4 v[180:183], v244, s[100:101]
	s_waitcnt lgkmcnt(4)
	v_mfma_f32_32x32x16_bf16 v[96:111], v[130:133], v[160:163], v[96:111]
	ds_read_b128 v[184:187], v152 offset:23136
	ds_write_b128 v128, v[188:191] offset:41472
	global_load_dwordx4 v[188:191], v245, s[100:101]
	s_waitcnt lgkmcnt(5)
	v_mfma_f32_32x32x16_bf16 v[80:95], v[130:133], v[164:167], v[80:95]
	ds_read_b128 v[156:159], v152 offset:27744
	ds_write_b128 v128, v[192:195] offset:46080
	global_load_dwordx4 v[192:195], v246, s[100:101]
	s_waitcnt lgkmcnt(6)
	v_mfma_f32_32x32x16_bf16 v[64:79], v[130:133], v[168:171], v[64:79]
	ds_read_b128 v[160:163], v152 offset:32352
	ds_write_b128 v128, v[196:199] offset:50688
	global_load_dwordx4 v[196:199], v247, s[100:101]
	s_waitcnt lgkmcnt(7)
	v_mfma_f32_32x32x16_bf16 v[48:63], v[130:133], v[172:175], v[48:63]
	ds_write_b128 v128, v[228:231] offset:55296
	global_load_dwordx4 v[228:231], v248, s[100:101]
	s_waitcnt lgkmcnt(6)
	v_mfma_f32_32x32x16_bf16 v[32:47], v[130:133], v[184:187], v[32:47]
	ds_write_b128 v128, v[232:235] offset:59904
	global_load_dwordx4 v[232:235], v249, s[100:101]
	s_waitcnt lgkmcnt(5)
	v_mfma_f32_32x32x16_bf16 v[16:31], v[130:133], v[156:159], v[16:31]
	ds_write_b128 v128, v[236:239] offset:64512
	global_load_dwordx4 v[236:239], v200, s[100:101]
	s_waitcnt lgkmcnt(4)
	v_mfma_f32_32x32x16_bf16 v[0:15], v[130:133], v[160:163], v[0:15]
	ds_write_b128 v153, v[240:243] offset:32256
	global_load_dwordx4 v[240:243], v201, s[100:101]
	global_load_dwordx4 v[130:133], v[150:151], off offset:1024
	v_lshl_add_u64 v[150:151], v[150:151], 0, s[26:27]
	s_waitcnt lgkmcnt(0)
	s_barrier
	ds_read_b128 v[156:159], v152 offset:36864
	ds_read_b128 v[160:163], v152 offset:41472
	ds_read_b128 v[164:167], v152 offset:46080
	ds_read_b128 v[168:171], v152 offset:50688
	s_waitcnt vmcnt(11) lgkmcnt(3)
	v_mfma_f32_32x32x16_bf16 v[112:127], v[142:145], v[156:159], v[112:127]
	ds_read_b128 v[172:175], v152 offset:55296
	s_waitcnt lgkmcnt(3)
	v_mfma_f32_32x32x16_bf16 v[96:111], v[142:145], v[160:163], v[96:111]
	ds_read_b128 v[184:187], v152 offset:59904
	s_add_u32 s100, s100, 0x80
	s_addc_u32 s101, s101, 0
	s_waitcnt lgkmcnt(3)
	v_mfma_f32_32x32x16_bf16 v[80:95], v[142:145], v[164:167], v[80:95]
	ds_read_b128 v[156:159], v152 offset:64512
	s_waitcnt lgkmcnt(3)
	v_mfma_f32_32x32x16_bf16 v[64:79], v[142:145], v[168:171], v[64:79]
	ds_read_b128 v[160:163], v154 offset:32256
	s_waitcnt lgkmcnt(3)
	v_mfma_f32_32x32x16_bf16 v[48:63], v[142:145], v[172:175], v[48:63]
	ds_read_b128 v[164:167], v152 offset:36896
	s_waitcnt lgkmcnt(3)
	v_mfma_f32_32x32x16_bf16 v[32:47], v[142:145], v[184:187], v[32:47]
	ds_read_b128 v[168:171], v152 offset:41504
	s_waitcnt lgkmcnt(3)
	v_mfma_f32_32x32x16_bf16 v[16:31], v[142:145], v[156:159], v[16:31]
	ds_read_b128 v[172:175], v152 offset:46112
	s_waitcnt lgkmcnt(3)
	v_mfma_f32_32x32x16_bf16 v[0:15], v[142:145], v[160:163], v[0:15]
	ds_read_b128 v[184:187], v152 offset:50720
	global_load_dwordx4 v[142:145], v[150:151], off offset:-2048
	s_waitcnt vmcnt(11) lgkmcnt(3)
	v_mfma_f32_32x32x16_bf16 v[112:127], v[138:141], v[164:167], v[112:127]
	ds_read_b128 v[156:159], v152 offset:55328
	s_waitcnt lgkmcnt(3)
	v_mfma_f32_32x32x16_bf16 v[96:111], v[138:141], v[168:171], v[96:111]
	ds_read_b128 v[160:163], v152 offset:59936
	s_waitcnt lgkmcnt(3)
	v_mfma_f32_32x32x16_bf16 v[80:95], v[138:141], v[172:175], v[80:95]
	ds_read_b128 v[164:167], v152 offset:64544
	s_waitcnt lgkmcnt(3)
	v_mfma_f32_32x32x16_bf16 v[64:79], v[138:141], v[184:187], v[64:79]
	ds_read_b128 v[168:171], v154 offset:32288
	s_waitcnt lgkmcnt(3)
	v_mfma_f32_32x32x16_bf16 v[48:63], v[138:141], v[156:159], v[48:63]
	ds_read_b128 v[172:175], v152 offset:36928
	s_waitcnt lgkmcnt(3)
	v_mfma_f32_32x32x16_bf16 v[32:47], v[138:141], v[160:163], v[32:47]
	ds_read_b128 v[184:187], v152 offset:41536
	s_waitcnt lgkmcnt(3)
	v_mfma_f32_32x32x16_bf16 v[16:31], v[138:141], v[164:167], v[16:31]
	ds_read_b128 v[156:159], v152 offset:46144
	s_waitcnt lgkmcnt(3)
	v_mfma_f32_32x32x16_bf16 v[0:15], v[138:141], v[168:171], v[0:15]
	ds_read_b128 v[160:163], v152 offset:50752
	global_load_dwordx4 v[138:141], v[150:151], off offset:-1024
	s_waitcnt vmcnt(11) lgkmcnt(3)
	v_mfma_f32_32x32x16_bf16 v[112:127], v[134:137], v[172:175], v[112:127]
	ds_read_b128 v[164:167], v152 offset:55360
	s_waitcnt lgkmcnt(3)
	v_mfma_f32_32x32x16_bf16 v[96:111], v[134:137], v[184:187], v[96:111]
	ds_read_b128 v[168:171], v152 offset:59968
	s_waitcnt lgkmcnt(3)
	v_mfma_f32_32x32x16_bf16 v[80:95], v[134:137], v[156:159], v[80:95]
	ds_read_b128 v[172:175], v152 offset:64576
	s_waitcnt lgkmcnt(3)
	v_mfma_f32_32x32x16_bf16 v[64:79], v[134:137], v[160:163], v[64:79]
	ds_read_b128 v[184:187], v154 offset:32320
	s_waitcnt lgkmcnt(3)
	v_mfma_f32_32x32x16_bf16 v[48:63], v[134:137], v[164:167], v[48:63]
	ds_read_b128 v[156:159], v152 offset:36960
	s_waitcnt lgkmcnt(3)
	v_mfma_f32_32x32x16_bf16 v[32:47], v[134:137], v[168:171], v[32:47]
	ds_read_b128 v[160:163], v152 offset:41568
	s_waitcnt lgkmcnt(3)
	v_mfma_f32_32x32x16_bf16 v[16:31], v[134:137], v[172:175], v[16:31]
	ds_read_b128 v[164:167], v152 offset:46176
	s_waitcnt lgkmcnt(3)
	v_mfma_f32_32x32x16_bf16 v[0:15], v[134:137], v[184:187], v[0:15]
	ds_read_b128 v[168:171], v152 offset:50784
	global_load_dwordx4 v[134:137], v[150:151], off
	s_waitcnt vmcnt(3) lgkmcnt(3)
	v_mfma_f32_32x32x16_bf16 v[112:127], v[130:133], v[156:159], v[112:127]
	ds_read_b128 v[172:175], v152 offset:55392
	ds_write_b128 v128, v[180:183]
	global_load_dwordx4 v[180:183], v244, s[100:101]
	s_waitcnt lgkmcnt(4)
	v_mfma_f32_32x32x16_bf16 v[96:111], v[130:133], v[160:163], v[96:111]
	ds_read_b128 v[184:187], v152 offset:60000
	ds_write_b128 v128, v[188:191] offset:4608
	global_load_dwordx4 v[188:191], v245, s[100:101]
	s_waitcnt lgkmcnt(5)
	v_mfma_f32_32x32x16_bf16 v[80:95], v[130:133], v[164:167], v[80:95]
	ds_read_b128 v[156:159], v152 offset:64608
	ds_write_b128 v128, v[192:195] offset:9216
	global_load_dwordx4 v[192:195], v246, s[100:101]
	s_waitcnt lgkmcnt(6)
	v_mfma_f32_32x32x16_bf16 v[64:79], v[130:133], v[168:171], v[64:79]
	ds_read_b128 v[160:163], v154 offset:32352
	ds_write_b128 v128, v[196:199] offset:13824
	global_load_dwordx4 v[196:199], v247, s[100:101]
	s_waitcnt lgkmcnt(7)
	v_mfma_f32_32x32x16_bf16 v[48:63], v[130:133], v[172:175], v[48:63]
	ds_write_b128 v128, v[228:231] offset:18432
	global_load_dwordx4 v[228:231], v248, s[100:101]
	s_waitcnt lgkmcnt(6)
	v_mfma_f32_32x32x16_bf16 v[32:47], v[130:133], v[184:187], v[32:47]
	ds_write_b128 v128, v[232:235] offset:23040
	global_load_dwordx4 v[232:235], v249, s[100:101]
	s_waitcnt lgkmcnt(5)
	v_mfma_f32_32x32x16_bf16 v[16:31], v[130:133], v[156:159], v[16:31]
	ds_write_b128 v128, v[236:239] offset:27648
	global_load_dwordx4 v[236:239], v200, s[100:101]
	s_waitcnt lgkmcnt(4)
	v_mfma_f32_32x32x16_bf16 v[0:15], v[130:133], v[160:163], v[0:15]
	ds_write_b128 v128, v[240:243] offset:32256
	global_load_dwordx4 v[240:243], v201, s[100:101]
	global_load_dwordx4 v[130:133], v[150:151], off offset:1024
	v_lshl_add_u64 v[150:151], v[150:151], 0, s[26:27]
	s_waitcnt lgkmcnt(0)
	s_barrier
	s_add_i32 s13, s13, 2
	s_branch .Lwf8_l9_top
.Lwf8_l9_pen:
	ds_read_b128 v[156:159], v152
	ds_read_b128 v[160:163], v152 offset:4608
	ds_read_b128 v[164:167], v152 offset:9216
	ds_read_b128 v[168:171], v152 offset:13824
	s_waitcnt vmcnt(11) lgkmcnt(3)
	v_mfma_f32_32x32x16_bf16 v[112:127], v[142:145], v[156:159], v[112:127]
	ds_read_b128 v[172:175], v152 offset:18432
	s_waitcnt lgkmcnt(3)
	v_mfma_f32_32x32x16_bf16 v[96:111], v[142:145], v[160:163], v[96:111]
	ds_read_b128 v[184:187], v152 offset:23040
	s_waitcnt lgkmcnt(3)
	v_mfma_f32_32x32x16_bf16 v[80:95], v[142:145], v[164:167], v[80:95]
	ds_read_b128 v[156:159], v152 offset:27648
	s_waitcnt lgkmcnt(3)
	v_mfma_f32_32x32x16_bf16 v[64:79], v[142:145], v[168:171], v[64:79]
	ds_read_b128 v[160:163], v152 offset:32256
	s_waitcnt lgkmcnt(3)
	v_mfma_f32_32x32x16_bf16 v[48:63], v[142:145], v[172:175], v[48:63]
	ds_read_b128 v[164:167], v152 offset:32
	s_waitcnt lgkmcnt(3)
	v_mfma_f32_32x32x16_bf16 v[32:47], v[142:145], v[184:187], v[32:47]
	ds_read_b128 v[168:171], v152 offset:4640
	s_waitcnt lgkmcnt(3)
	v_mfma_f32_32x32x16_bf16 v[16:31], v[142:145], v[156:159], v[16:31]
	ds_read_b128 v[172:175], v152 offset:9248
	s_waitcnt lgkmcnt(3)
	v_mfma_f32_32x32x16_bf16 v[0:15], v[142:145], v[160:163], v[0:15]
	ds_read_b128 v[184:187], v152 offset:13856
	global_load_dwordx4 v[142:145], v[150:151], off offset:-2048
	s_waitcnt vmcnt(11) lgkmcnt(3)
	v_mfma_f32_32x32x16_bf16 v[112:127], v[138:141], v[164:167], v[112:127]
	ds_read_b128 v[156:159], v152 offset:18464
	s_waitcnt lgkmcnt(3)
	v_mfma_f32_32x32x16_bf16 v[96:111], v[138:141], v[168:171], v[96:111]
	ds_read_b128 v[160:163], v152 offset:23072
	s_waitcnt lgkmcnt(3)
	v_mfma_f32_32x32x16_bf16 v[80:95], v[138:141], v[172:175], v[80:95]
	ds_read_b128 v[164:167], v152 offset:27680
	s_waitcnt lgkmcnt(3)
	v_mfma_f32_32x32x16_bf16 v[64:79], v[138:141], v[184:187], v[64:79]
	ds_read_b128 v[168:171], v152 offset:32288
	s_waitcnt lgkmcnt(3)
	v_mfma_f32_32x32x16_bf16 v[48:63], v[138:141], v[156:159], v[48:63]
	ds_read_b128 v[172:175], v152 offset:64
	s_waitcnt lgkmcnt(3)
	v_mfma_f32_32x32x16_bf16 v[32:47], v[138:141], v[160:163], v[32:47]
	ds_read_b128 v[184:187], v152 offset:4672
	s_waitcnt lgkmcnt(3)
	v_mfma_f32_32x32x16_bf16 v[16:31], v[138:141], v[164:167], v[16:31]
	ds_read_b128 v[156:159], v152 offset:9280
	s_waitcnt lgkmcnt(3)
	v_mfma_f32_32x32x16_bf16 v[0:15], v[138:141], v[168:171], v[0:15]
	ds_read_b128 v[160:163], v152 offset:13888
	global_load_dwordx4 v[138:141], v[150:151], off offset:-1024
	s_waitcnt vmcnt(11) lgkmcnt(3)
	v_mfma_f32_32x32x16_bf16 v[112:127], v[134:137], v[172:175], v[112:127]
	ds_read_b128 v[164:167], v152 offset:18496
	s_waitcnt lgkmcnt(3)
	v_mfma_f32_32x32x16_bf16 v[96:111], v[134:137], v[184:187], v[96:111]
	ds_read_b128 v[168:171], v152 offset:23104
	s_waitcnt lgkmcnt(3)
	v_mfma_f32_32x32x16_bf16 v[80:95], v[134:137], v[156:159], v[80:95]
	ds_read_b128 v[172:175], v152 offset:27712
	s_waitcnt lgkmcnt(3)
	v_mfma_f32_32x32x16_bf16 v[64:79], v[134:137], v[160:163], v[64:79]
	ds_read_b128 v[184:187], v152 offset:32320
	s_waitcnt lgkmcnt(3)
	v_mfma_f32_32x32x16_bf16 v[48:63], v[134:137], v[164:167], v[48:63]
	ds_read_b128 v[156:159], v152 offset:96
	s_waitcnt lgkmcnt(3)
	v_mfma_f32_32x32x16_bf16 v[32:47], v[134:137], v[168:171], v[32:47]
	ds_read_b128 v[160:163], v152 offset:4704
	s_waitcnt lgkmcnt(3)
	v_mfma_f32_32x32x16_bf16 v[16:31], v[134:137], v[172:175], v[16:31]
	ds_read_b128 v[164:167], v152 offset:9312
	s_waitcnt lgkmcnt(3)
	v_mfma_f32_32x32x16_bf16 v[0:15], v[134:137], v[184:187], v[0:15]
	ds_read_b128 v[168:171], v152 offset:13920
	global_load_dwordx4 v[134:137], v[150:151], off
	s_waitcnt vmcnt(3) lgkmcnt(3)
	v_mfma_f32_32x32x16_bf16 v[112:127], v[130:133], v[156:159], v[112:127]
	ds_read_b128 v[172:175], v152 offset:18528
	ds_write_b128 v128, v[180:183] offset:36864
	s_waitcnt lgkmcnt(4)
	v_mfma_f32_32x32x16_bf16 v[96:111], v[130:133], v[160:163], v[96:111]
	ds_read_b128 v[184:187], v152 offset:23136
	ds_write_b128 v128, v[188:191] offset:41472
	s_waitcnt lgkmcnt(5)
	v_mfma_f32_32x32x16_bf16 v[80:95], v[130:133], v[164:167], v[80:95]
	ds_read_b128 v[156:159], v152 offset:27744
	ds_write_b128 v128, v[192:195] offset:46080
	s_waitcnt lgkmcnt(6)
	v_mfma_f32_32x32x16_bf16 v[64:79], v[130:133], v[168:171], v[64:79]
	ds_read_b128 v[160:163], v152 offset:32352
	ds_write_b128 v128, v[196:199] offset:50688
	s_waitcnt lgkmcnt(7)
	v_mfma_f32_32x32x16_bf16 v[48:63], v[130:133], v[172:175], v[48:63]
	ds_write_b128 v128, v[228:231] offset:55296
	s_waitcnt lgkmcnt(6)
	v_mfma_f32_32x32x16_bf16 v[32:47], v[130:133], v[184:187], v[32:47]
	ds_write_b128 v128, v[232:235] offset:59904
	s_waitcnt lgkmcnt(5)
	v_mfma_f32_32x32x16_bf16 v[16:31], v[130:133], v[156:159], v[16:31]
	ds_write_b128 v128, v[236:239] offset:64512
	s_waitcnt lgkmcnt(4)
	v_mfma_f32_32x32x16_bf16 v[0:15], v[130:133], v[160:163], v[0:15]
	ds_write_b128 v153, v[240:243] offset:32256
	global_load_dwordx4 v[130:133], v[150:151], off offset:1024
	v_lshl_add_u64 v[150:151], v[150:151], 0, s[26:27]
	s_waitcnt lgkmcnt(0)
	s_barrier
	ds_read_b128 v[156:159], v152 offset:36864
	ds_read_b128 v[160:163], v152 offset:41472
	ds_read_b128 v[164:167], v152 offset:46080
	ds_read_b128 v[168:171], v152 offset:50688
	s_waitcnt vmcnt(3) lgkmcnt(3)
	v_mfma_f32_32x32x16_bf16 v[112:127], v[142:145], v[156:159], v[112:127]
	ds_read_b128 v[172:175], v152 offset:55296
	s_waitcnt lgkmcnt(3)
	v_mfma_f32_32x32x16_bf16 v[96:111], v[142:145], v[160:163], v[96:111]
	ds_read_b128 v[184:187], v152 offset:59904
	s_waitcnt lgkmcnt(3)
	v_mfma_f32_32x32x16_bf16 v[80:95], v[142:145], v[164:167], v[80:95]
	ds_read_b128 v[156:159], v152 offset:64512
	s_waitcnt lgkmcnt(3)
	v_mfma_f32_32x32x16_bf16 v[64:79], v[142:145], v[168:171], v[64:79]
	ds_read_b128 v[160:163], v154 offset:32256
	s_waitcnt lgkmcnt(3)
	v_mfma_f32_32x32x16_bf16 v[48:63], v[142:145], v[172:175], v[48:63]
	ds_read_b128 v[164:167], v152 offset:36896
	s_waitcnt lgkmcnt(3)
	v_mfma_f32_32x32x16_bf16 v[32:47], v[142:145], v[184:187], v[32:47]
	ds_read_b128 v[168:171], v152 offset:41504
	s_waitcnt lgkmcnt(3)
	v_mfma_f32_32x32x16_bf16 v[16:31], v[142:145], v[156:159], v[16:31]
	ds_read_b128 v[172:175], v152 offset:46112
	s_waitcnt lgkmcnt(3)
	v_mfma_f32_32x32x16_bf16 v[0:15], v[142:145], v[160:163], v[0:15]
	ds_read_b128 v[184:187], v152 offset:50720
	s_waitcnt vmcnt(2) lgkmcnt(3)
	v_mfma_f32_32x32x16_bf16 v[112:127], v[138:141], v[164:167], v[112:127]
	ds_read_b128 v[156:159], v152 offset:55328
	s_waitcnt lgkmcnt(3)
	v_mfma_f32_32x32x16_bf16 v[96:111], v[138:141], v[168:171], v[96:111]
	ds_read_b128 v[160:163], v152 offset:59936
	s_waitcnt lgkmcnt(3)
	v_mfma_f32_32x32x16_bf16 v[80:95], v[138:141], v[172:175], v[80:95]
	ds_read_b128 v[164:167], v152 offset:64544
	s_waitcnt lgkmcnt(3)
	v_mfma_f32_32x32x16_bf16 v[64:79], v[138:141], v[184:187], v[64:79]
	ds_read_b128 v[168:171], v154 offset:32288
	s_waitcnt lgkmcnt(3)
	v_mfma_f32_32x32x16_bf16 v[48:63], v[138:141], v[156:159], v[48:63]
	ds_read_b128 v[172:175], v152 offset:36928
	s_waitcnt lgkmcnt(3)
	v_mfma_f32_32x32x16_bf16 v[32:47], v[138:141], v[160:163], v[32:47]
	ds_read_b128 v[184:187], v152 offset:41536
	s_waitcnt lgkmcnt(3)
	v_mfma_f32_32x32x16_bf16 v[16:31], v[138:141], v[164:167], v[16:31]
	ds_read_b128 v[156:159], v152 offset:46144
	s_waitcnt lgkmcnt(3)
	v_mfma_f32_32x32x16_bf16 v[0:15], v[138:141], v[168:171], v[0:15]
	ds_read_b128 v[160:163], v152 offset:50752
	s_waitcnt vmcnt(1) lgkmcnt(3)
	v_mfma_f32_32x32x16_bf16 v[112:127], v[134:137], v[172:175], v[112:127]
	ds_read_b128 v[164:167], v152 offset:55360
	s_waitcnt lgkmcnt(3)
	v_mfma_f32_32x32x16_bf16 v[96:111], v[134:137], v[184:187], v[96:111]
	ds_read_b128 v[168:171], v152 offset:59968
	s_waitcnt lgkmcnt(3)
	v_mfma_f32_32x32x16_bf16 v[80:95], v[134:137], v[156:159], v[80:95]
	ds_read_b128 v[172:175], v152 offset:64576
	s_waitcnt lgkmcnt(3)
	v_mfma_f32_32x32x16_bf16 v[64:79], v[134:137], v[160:163], v[64:79]
	ds_read_b128 v[184:187], v154 offset:32320
	s_waitcnt lgkmcnt(3)
	v_mfma_f32_32x32x16_bf16 v[48:63], v[134:137], v[164:167], v[48:63]
	ds_read_b128 v[156:159], v152 offset:36960
	s_waitcnt lgkmcnt(3)
	v_mfma_f32_32x32x16_bf16 v[32:47], v[134:137], v[168:171], v[32:47]
	ds_read_b128 v[160:163], v152 offset:41568
	s_waitcnt lgkmcnt(3)
	v_mfma_f32_32x32x16_bf16 v[16:31], v[134:137], v[172:175], v[16:31]
	ds_read_b128 v[164:167], v152 offset:46176
	s_waitcnt lgkmcnt(3)
	v_mfma_f32_32x32x16_bf16 v[0:15], v[134:137], v[184:187], v[0:15]
	ds_read_b128 v[168:171], v152 offset:50784
	s_waitcnt vmcnt(0) lgkmcnt(3)
	v_mfma_f32_32x32x16_bf16 v[112:127], v[130:133], v[156:159], v[112:127]
	ds_read_b128 v[172:175], v152 offset:55392
	s_waitcnt lgkmcnt(3)
	v_mfma_f32_32x32x16_bf16 v[96:111], v[130:133], v[160:163], v[96:111]
	ds_read_b128 v[184:187], v152 offset:60000
	s_waitcnt lgkmcnt(3)
	v_mfma_f32_32x32x16_bf16 v[80:95], v[130:133], v[164:167], v[80:95]
	ds_read_b128 v[156:159], v152 offset:64608
	s_waitcnt lgkmcnt(3)
	v_mfma_f32_32x32x16_bf16 v[64:79], v[130:133], v[168:171], v[64:79]
	ds_read_b128 v[160:163], v154 offset:32352
	s_waitcnt lgkmcnt(3)
	v_mfma_f32_32x32x16_bf16 v[48:63], v[130:133], v[172:175], v[48:63]
	s_waitcnt lgkmcnt(2)
	v_mfma_f32_32x32x16_bf16 v[32:47], v[130:133], v[184:187], v[32:47]
	s_waitcnt lgkmcnt(1)
	v_mfma_f32_32x32x16_bf16 v[16:31], v[130:133], v[156:159], v[16:31]
	s_waitcnt lgkmcnt(0)
	v_mfma_f32_32x32x16_bf16 v[0:15], v[130:133], v[160:163], v[0:15]
	s_waitcnt lgkmcnt(0)
	s_barrier
	s_nop 7
	s_nop 7
	s_branch .LBB0_2050
